# conv-gate phase: lane mapping changed so every load/store instruction covers whole 128-byte lines; its u loads non-temporal
# baseline (speedup 1.0000x reference)
; __device__ __forceinline__ float bflo(unsigned w) { return __uint_as_float(w << 16); }
; __device__ __forceinline__ float bfhi(unsigned w) { return __uint_as_float(w & 0xffff0000u); }
; __device__ __forceinline__ void convgate_phase(const bf16_t* U, bf16_t* H, int rows, const float* ck, int gw, int NGW, int lane) {
;     for (int row = gw; row < rows; row += NGW) {
;         const bool lat = row < ML; const int t = lat ? (row & (SEQ - 1)) : ((row - ML) & (CL - 1)); const int L = lat ? SEQ : CL;
;         const bool hasp = t > 0, hasn = t < L - 1;
;         const bf16_t* ur = U + (size_t)row * 3072;
;         u32x4 bq[2], cq[2], vq[2], cp[2], vp[2], cn[2], vn[2];
; #pragma unroll
;         for (int hf = 0; hf < 2; ++hf) {
;             const int c0 = lane * 16 + hf * 8;
;             bq[hf] = *(const u32x4*)(ur + c0); cq[hf] = *(const u32x4*)(ur + 1024 + c0); vq[hf] = *(const u32x4*)(ur + 2048 + c0);
;             cp[hf] = (u32x4){0, 0, 0, 0}; vp[hf] = cp[hf]; cn[hf] = cp[hf]; vn[hf] = cp[hf];
;             if (hasp) { cp[hf] = *(const u32x4*)(ur - 3072 + 1024 + c0); vp[hf] = *(const u32x4*)(ur - 3072 + 2048 + c0); }
;             if (hasn) { cn[hf] = *(const u32x4*)(ur + 3072 + 1024 + c0); vn[hf] = *(const u32x4*)(ur + 3072 + 2048 + c0); }
;         }
; #pragma unroll
;         for (int hf = 0; hf < 2; ++hf) {
;             const int c0 = lane * 16 + hf * 8;
;             u32x4 ow;
; #pragma unroll
;             for (int e = 0; e < 4; ++e) {
;                 const f32x2 w0 = *(const f32x2*)(ck + c0 + 2 * e), w1 = *(const f32x2*)(ck + D + c0 + 2 * e), w2 = *(const f32x2*)(ck + 2 * D + c0 + 2 * e);
;                 const float lo = bflo(bq[hf][e]) * (w0[0] * (bflo(cp[hf][e]) * bflo(vp[hf][e])) + w1[0] * (bflo(cq[hf][e]) * bflo(vq[hf][e])) + w2[0] * (bflo(cn[hf][e]) * bflo(vn[hf][e])));
;                 const float hi = bfhi(bq[hf][e]) * (w0[1] * (bfhi(cp[hf][e]) * bfhi(vp[hf][e])) + w1[1] * (bfhi(cq[hf][e]) * bfhi(vq[hf][e])) + w2[1] * (bfhi(cn[hf][e]) * bfhi(vn[hf][e])));
.LBB0_893:
	s_andn2_b64 vcc, exec, s[4:5]
	s_cbranch_vccnz .LBB0_906
	s_cmp_ge_i32 s16, s65
	v_mov_b32_e32 v0, v196
	s_cbranch_scc1 .LBB0_906
	s_load_dwordx2 s[0:1], s[62:63], 0x50
	s_lshl_b64 s[4:5], s[72:73], 12
	v_and_b32_e32 v3, 63, v196
	v_lshlrev_b32_e32 v1, 4, v3
	v_add_u32_e32 v2, 0x1000, v1
	v_lshlrev_b32_e32 v3, 5, v3
	s_lshr_b32 s10, s65, 11
	s_mul_i32 s11, s16, s10
	s_mov_b32 s14, 0xffff0000
	s_movk_i32 s3, 0x7ff
	s_movk_i32 s13, 0xff
	s_waitcnt lgkmcnt(0)
	s_add_u32 s0, s0, s4
	s_addc_u32 s1, s1, s5
	s_add_u32 s22, s0, 0x1000
	s_addc_u32 s23, s1, 0
	s_add_u32 s24, s0, 0x2000
	s_addc_u32 s25, s1, 0
	global_load_dwordx4 v[4:7], v3, s[0:1]
	global_load_dwordx4 v[8:11], v3, s[0:1] offset:16
	global_load_dwordx4 v[12:15], v3, s[0:1] offset:2048
	global_load_dwordx4 v[16:19], v3, s[0:1] offset:2064
	global_load_dwordx4 v[20:23], v3, s[22:23]
	global_load_dwordx4 v[24:27], v3, s[22:23] offset:16
	global_load_dwordx4 v[28:31], v3, s[22:23] offset:2048
	global_load_dwordx4 v[32:35], v3, s[22:23] offset:2064
	global_load_dwordx4 v[36:39], v3, s[24:25]
	global_load_dwordx4 v[40:43], v3, s[24:25] offset:16
	global_load_dwordx4 v[44:47], v3, s[24:25] offset:2048
	global_load_dwordx4 v[48:51], v3, s[24:25] offset:2064
	s_mul_i32 s12, s11, 0x1800
	s_add_u32 s6, s54, 0x9400000
	s_addc_u32 s7, s55, 0
	s_add_u32 s6, s6, s12
	s_addc_u32 s7, s7, 0
	s_sub_u32 s4, s6, 0x1800
	s_subb_u32 s5, s7, 0
	s_lshl_b32 s12, s11, 11
	s_add_u32 s8, s54, 0x7000000
	s_addc_u32 s9, s55, 0
	s_add_u32 s8, s8, s12
	s_addc_u32 s9, s9, 0
	s_cmp_eq_u32 s10, 9
	s_cbranch_scc0 .Lcg8_top
.Lcg9_top:
	global_load_dwordx4 v[114:117], v1, s[4:5] offset:2048 nt
	global_load_dwordx4 v[118:121], v1, s[4:5] offset:3072 nt
	global_load_dwordx4 v[122:125], v2, s[4:5] nt
	global_load_dwordx4 v[126:129], v2, s[4:5] offset:1024 nt
	s_add_u32 s4, s4, 0x1800
	s_addc_u32 s5, s5, 0
	global_load_dwordx4 v[130:133], v1, s[4:5] offset:2048 nt
	global_load_dwordx4 v[134:137], v1, s[4:5] offset:3072 nt
	global_load_dwordx4 v[138:141], v2, s[4:5] nt
	global_load_dwordx4 v[142:145], v2, s[4:5] offset:1024 nt
	s_add_u32 s4, s4, 0x1800
	s_addc_u32 s5, s5, 0
	global_load_dwordx4 v[146:149], v1, s[6:7] nt
	global_load_dwordx4 v[150:153], v1, s[6:7] offset:1024 nt
	s_add_u32 s6, s6, 0x1800
	s_addc_u32 s7, s7, 0
	global_load_dwordx4 v[160:163], v1, s[4:5] offset:2048 nt
	global_load_dwordx4 v[164:167], v1, s[4:5] offset:3072 nt
	global_load_dwordx4 v[168:171], v2, s[4:5] nt
	global_load_dwordx4 v[172:175], v2, s[4:5] offset:1024 nt
	s_add_u32 s4, s4, 0x1800
	s_addc_u32 s5, s5, 0
	global_load_dwordx4 v[176:179], v1, s[6:7] nt
	global_load_dwordx4 v[180:183], v1, s[6:7] offset:1024 nt
	s_add_u32 s6, s6, 0x1800
	s_addc_u32 s7, s7, 0
	s_waitcnt vmcnt(12)
	v_lshlrev_b32_e32 v202, 16, v114
	v_and_b32_e32 v203, s14, v114
	v_lshlrev_b32_e32 v204, 16, v122
	v_and_b32_e32 v205, s14, v122
	v_pk_mul_f32 v[52:53], v[202:203], v[204:205]
	v_lshlrev_b32_e32 v206, 16, v115
	v_and_b32_e32 v207, s14, v115
	v_lshlrev_b32_e32 v208, 16, v123
	v_and_b32_e32 v209, s14, v123
	v_pk_mul_f32 v[54:55], v[206:207], v[208:209]
	v_lshlrev_b32_e32 v210, 16, v116
	v_and_b32_e32 v211, s14, v116
	v_lshlrev_b32_e32 v212, 16, v124
	v_and_b32_e32 v213, s14, v124
	v_pk_mul_f32 v[56:57], v[210:211], v[212:213]
	v_lshlrev_b32_e32 v202, 16, v117
	v_and_b32_e32 v203, s14, v117
	v_lshlrev_b32_e32 v204, 16, v125
	v_and_b32_e32 v205, s14, v125
	v_pk_mul_f32 v[58:59], v[202:203], v[204:205]
	v_lshlrev_b32_e32 v206, 16, v118
	v_and_b32_e32 v207, s14, v118
	v_lshlrev_b32_e32 v208, 16, v126
	v_and_b32_e32 v209, s14, v126
	v_pk_mul_f32 v[60:61], v[206:207], v[208:209]
	v_lshlrev_b32_e32 v210, 16, v119
	v_and_b32_e32 v211, s14, v119
	v_lshlrev_b32_e32 v212, 16, v127
	v_and_b32_e32 v213, s14, v127
	v_pk_mul_f32 v[62:63], v[210:211], v[212:213]
	v_lshlrev_b32_e32 v202, 16, v120
	v_and_b32_e32 v203, s14, v120
	v_lshlrev_b32_e32 v204, 16, v128
	v_and_b32_e32 v205, s14, v128
	v_pk_mul_f32 v[64:65], v[202:203], v[204:205]
	v_lshlrev_b32_e32 v206, 16, v121
	v_and_b32_e32 v207, s14, v121
	v_lshlrev_b32_e32 v208, 16, v129
	v_and_b32_e32 v209, s14, v129
	v_pk_mul_f32 v[66:67], v[206:207], v[208:209]
	global_load_dwordx4 v[114:117], v1, s[4:5] offset:2048 nt
	global_load_dwordx4 v[118:121], v1, s[4:5] offset:3072 nt
	global_load_dwordx4 v[122:125], v2, s[4:5] nt
	global_load_dwordx4 v[126:129], v2, s[4:5] offset:1024 nt
	s_add_u32 s4, s4, 0x1800
	s_addc_u32 s5, s5, 0
	global_load_dwordx4 v[226:229], v1, s[6:7] nt
	global_load_dwordx4 v[230:233], v1, s[6:7] offset:1024 nt
	s_add_u32 s6, s6, 0x1800
	s_addc_u32 s7, s7, 0
	s_waitcnt vmcnt(14)
; __device__ __forceinline__ unsigned cvt_pk_bf16(float lo, float hi) { unsigned r; asm volatile("v_cvt_pk_bf16_f32 %0, %1, %2" : "=v"(r) : "v"(lo), "v"(hi)); return r; }
; __device__ __forceinline__ float bflo(unsigned w) { return __uint_as_float(w << 16); }
; __device__ __forceinline__ float bfhi(unsigned w) { return __uint_as_float(w & 0xffff0000u); }
; __device__ __forceinline__ void convgate_phase(const bf16_t* U, bf16_t* H, int rows, const float* ck, int gw, int NGW, int lane) {
;     ...
;             if (hasp) { cp[hf] = *(const u32x4*)(ur - 3072 + 1024 + c0); vp[hf] = *(const u32x4*)(ur - 3072 + 2048 + c0); }
;             if (hasn) { cn[hf] = *(const u32x4*)(ur + 3072 + 1024 + c0); vn[hf] = *(const u32x4*)(ur + 3072 + 2048 + c0); }
;         }
; #pragma unroll
;         for (int hf = 0; hf < 2; ++hf) {
;             const int c0 = lane * 16 + hf * 8;
;             u32x4 ow;
; #pragma unroll
;             for (int e = 0; e < 4; ++e) {
;                 const f32x2 w0 = *(const f32x2*)(ck + c0 + 2 * e), w1 = *(const f32x2*)(ck + D + c0 + 2 * e), w2 = *(const f32x2*)(ck + 2 * D + c0 + 2 * e);
;                 const float lo = bflo(bq[hf][e]) * (w0[0] * (bflo(cp[hf][e]) * bflo(vp[hf][e])) + w1[0] * (bflo(cq[hf][e]) * bflo(vq[hf][e])) + w2[0] * (bflo(cn[hf][e]) * bflo(vn[hf][e])));
;                 const float hi = bfhi(bq[hf][e]) * (w0[1] * (bfhi(cp[hf][e]) * bfhi(vp[hf][e])) + w1[1] * (bfhi(cq[hf][e]) * bfhi(vq[hf][e])) + w2[1] * (bfhi(cn[hf][e]) * bfhi(vn[hf][e])));
;                 ow[e] = cvt_pk_bf16(lo, hi);
	v_lshlrev_b32_e32 v202, 16, v130
	v_and_b32_e32 v203, s14, v130
	v_lshlrev_b32_e32 v204, 16, v138
	v_and_b32_e32 v205, s14, v138
	v_pk_mul_f32 v[68:69], v[202:203], v[204:205]
	v_lshlrev_b32_e32 v206, 16, v131
	v_and_b32_e32 v207, s14, v131
	v_lshlrev_b32_e32 v208, 16, v139
	v_and_b32_e32 v209, s14, v139
	v_pk_mul_f32 v[70:71], v[206:207], v[208:209]
	v_lshlrev_b32_e32 v210, 16, v132
	v_and_b32_e32 v211, s14, v132
	v_lshlrev_b32_e32 v212, 16, v140
	v_and_b32_e32 v213, s14, v140
	v_pk_mul_f32 v[72:73], v[210:211], v[212:213]
	v_lshlrev_b32_e32 v202, 16, v133
	v_and_b32_e32 v203, s14, v133
	v_lshlrev_b32_e32 v204, 16, v141
	v_and_b32_e32 v205, s14, v141
	v_pk_mul_f32 v[74:75], v[202:203], v[204:205]
	v_lshlrev_b32_e32 v206, 16, v134
	v_and_b32_e32 v207, s14, v134
	v_lshlrev_b32_e32 v208, 16, v142
	v_and_b32_e32 v209, s14, v142
	v_pk_mul_f32 v[76:77], v[206:207], v[208:209]
	v_lshlrev_b32_e32 v210, 16, v135
	v_and_b32_e32 v211, s14, v135
	v_lshlrev_b32_e32 v212, 16, v143
	v_and_b32_e32 v213, s14, v143
	v_pk_mul_f32 v[78:79], v[210:211], v[212:213]
	v_lshlrev_b32_e32 v202, 16, v136
	v_and_b32_e32 v203, s14, v136
	v_lshlrev_b32_e32 v204, 16, v144
	v_and_b32_e32 v205, s14, v144
	v_pk_mul_f32 v[80:81], v[202:203], v[204:205]
	v_lshlrev_b32_e32 v206, 16, v137
	v_and_b32_e32 v207, s14, v137
	v_lshlrev_b32_e32 v208, 16, v145
	v_and_b32_e32 v209, s14, v145
	v_pk_mul_f32 v[82:83], v[206:207], v[208:209]
	global_load_dwordx4 v[130:133], v1, s[4:5] offset:2048 nt
	global_load_dwordx4 v[134:137], v1, s[4:5] offset:3072 nt
	global_load_dwordx4 v[138:141], v2, s[4:5] nt
	global_load_dwordx4 v[142:145], v2, s[4:5] offset:1024 nt
	s_add_u32 s4, s4, 0x1800
	s_addc_u32 s5, s5, 0
	s_waitcnt vmcnt(12)
	v_lshlrev_b32_e32 v202, 16, v160
	v_and_b32_e32 v203, s14, v160
	v_lshlrev_b32_e32 v204, 16, v168
	v_and_b32_e32 v205, s14, v168
	v_pk_mul_f32 v[98:99], v[202:203], v[204:205]
	v_lshlrev_b32_e32 v206, 16, v161
	v_and_b32_e32 v207, s14, v161
	v_lshlrev_b32_e32 v208, 16, v169
	v_and_b32_e32 v209, s14, v169
	v_pk_mul_f32 v[100:101], v[206:207], v[208:209]
	v_lshlrev_b32_e32 v210, 16, v162
	v_and_b32_e32 v211, s14, v162
	v_lshlrev_b32_e32 v212, 16, v170
	v_and_b32_e32 v213, s14, v170
	v_pk_mul_f32 v[102:103], v[210:211], v[212:213]
	v_lshlrev_b32_e32 v202, 16, v163
	v_and_b32_e32 v203, s14, v163
	v_lshlrev_b32_e32 v204, 16, v171
	v_and_b32_e32 v205, s14, v171
	v_pk_mul_f32 v[104:105], v[202:203], v[204:205]
	v_lshlrev_b32_e32 v206, 16, v164
	v_and_b32_e32 v207, s14, v164
	v_lshlrev_b32_e32 v208, 16, v172
	v_and_b32_e32 v209, s14, v172
	v_pk_mul_f32 v[106:107], v[206:207], v[208:209]
	v_lshlrev_b32_e32 v210, 16, v165
	v_and_b32_e32 v211, s14, v165
	v_lshlrev_b32_e32 v212, 16, v173
	v_and_b32_e32 v213, s14, v173
	v_pk_mul_f32 v[108:109], v[210:211], v[212:213]
	v_lshlrev_b32_e32 v202, 16, v166
	v_and_b32_e32 v203, s14, v166
	v_lshlrev_b32_e32 v204, 16, v174
	v_and_b32_e32 v205, s14, v174
	v_pk_mul_f32 v[110:111], v[202:203], v[204:205]
	v_lshlrev_b32_e32 v206, 16, v167
	v_and_b32_e32 v207, s14, v167
	v_lshlrev_b32_e32 v208, 16, v175
	v_and_b32_e32 v209, s14, v175
	v_pk_mul_f32 v[112:113], v[206:207], v[208:209]
	global_load_dwordx4 v[160:163], v1, s[4:5] offset:2048 nt
	global_load_dwordx4 v[164:167], v1, s[4:5] offset:3072 nt
	global_load_dwordx4 v[168:171], v2, s[4:5] nt
	global_load_dwordx4 v[172:175], v2, s[4:5] offset:1024 nt
	s_add_u32 s4, s4, 0x1800
	s_addc_u32 s5, s5, 0
	s_add_i32 s12, s11, 0
	s_cmp_lt_u32 s12, 0x4000
	s_cselect_b32 s29, s3, s13
	s_and_b32 s27, s12, s29
	v_pk_mul_f32 v[234:235], v[20:21], v[68:69]
	v_pk_mul_f32 v[236:237], v[22:23], v[70:71]
	v_pk_mul_f32 v[238:239], v[24:25], v[72:73]
	v_pk_mul_f32 v[240:241], v[26:27], v[74:75]
	v_pk_mul_f32 v[242:243], v[28:29], v[76:77]
	v_pk_mul_f32 v[244:245], v[30:31], v[78:79]
	v_pk_mul_f32 v[246:247], v[32:33], v[80:81]
	v_pk_mul_f32 v[248:249], v[34:35], v[82:83]
	s_cmp_eq_u32 s27, 0
	s_cbranch_scc1 .Lcg9_np0
	v_pk_fma_f32 v[234:235], v[4:5], v[52:53], v[234:235]
	v_pk_fma_f32 v[236:237], v[6:7], v[54:55], v[236:237]
	v_pk_fma_f32 v[238:239], v[8:9], v[56:57], v[238:239]
	v_pk_fma_f32 v[240:241], v[10:11], v[58:59], v[240:241]
	v_pk_fma_f32 v[242:243], v[12:13], v[60:61], v[242:243]
	v_pk_fma_f32 v[244:245], v[14:15], v[62:63], v[244:245]
	v_pk_fma_f32 v[246:247], v[16:17], v[64:65], v[246:247]
	v_pk_fma_f32 v[248:249], v[18:19], v[66:67], v[248:249]

; __device__ __forceinline__ unsigned cvt_pk_bf16(float lo, float hi) { unsigned r; asm volatile("v_cvt_pk_bf16_f32 %0, %1, %2" : "=v"(r) : "v"(lo), "v"(hi)); return r; }
; __device__ __forceinline__ float bflo(unsigned w) { return __uint_as_float(w << 16); }
; __device__ __forceinline__ float bfhi(unsigned w) { return __uint_as_float(w & 0xffff0000u); }
; __device__ __forceinline__ void convgate_phase(const bf16_t* U, bf16_t* H, int rows, const float* ck, int gw, int NGW, int lane) {
;     ...
;             for (int e = 0; e < 4; ++e) {
;                 const f32x2 w0 = *(const f32x2*)(ck + c0 + 2 * e), w1 = *(const f32x2*)(ck + D + c0 + 2 * e), w2 = *(const f32x2*)(ck + 2 * D + c0 + 2 * e);
;                 const float lo = bflo(bq[hf][e]) * (w0[0] * (bflo(cp[hf][e]) * bflo(vp[hf][e])) + w1[0] * (bflo(cq[hf][e]) * bflo(vq[hf][e])) + w2[0] * (bflo(cn[hf][e]) * bflo(vn[hf][e])));
;                 const float hi = bfhi(bq[hf][e]) * (w0[1] * (bfhi(cp[hf][e]) * bfhi(vp[hf][e])) + w1[1] * (bfhi(cq[hf][e]) * bfhi(vq[hf][e])) + w2[1] * (bfhi(cn[hf][e]) * bfhi(vn[hf][e])));
;                 ow[e] = cvt_pk_bf16(lo, hi);
;             }
;             *(u32x4*)(H + (size_t)row * D + c0) = ow;
.Lcg9_nn0:
	v_lshlrev_b32_e32 v202, 16, v146
	v_and_b32_e32 v203, s14, v146
	v_pk_mul_f32 v[234:235], v[234:235], v[202:203]
	v_lshlrev_b32_e32 v206, 16, v147
	v_and_b32_e32 v207, s14, v147
	v_pk_mul_f32 v[236:237], v[236:237], v[206:207]
	v_lshlrev_b32_e32 v210, 16, v148
	v_and_b32_e32 v211, s14, v148
	v_pk_mul_f32 v[238:239], v[238:239], v[210:211]
	v_lshlrev_b32_e32 v202, 16, v149
	v_and_b32_e32 v203, s14, v149
	v_pk_mul_f32 v[240:241], v[240:241], v[202:203]
	v_lshlrev_b32_e32 v206, 16, v150
	v_and_b32_e32 v207, s14, v150
	v_pk_mul_f32 v[242:243], v[242:243], v[206:207]
	v_lshlrev_b32_e32 v210, 16, v151
	v_and_b32_e32 v211, s14, v151
	v_pk_mul_f32 v[244:245], v[244:245], v[210:211]
	v_lshlrev_b32_e32 v202, 16, v152
	v_and_b32_e32 v203, s14, v152
	v_pk_mul_f32 v[246:247], v[246:247], v[202:203]
	v_lshlrev_b32_e32 v206, 16, v153
	v_and_b32_e32 v207, s14, v153
	v_pk_mul_f32 v[248:249], v[248:249], v[206:207]
	v_cvt_pk_bf16_f32 v84, v234, v235
	v_cvt_pk_bf16_f32 v85, v236, v237
	v_cvt_pk_bf16_f32 v86, v238, v239
	v_cvt_pk_bf16_f32 v87, v240, v241
	v_cvt_pk_bf16_f32 v88, v242, v243
	v_cvt_pk_bf16_f32 v89, v244, v245
	v_cvt_pk_bf16_f32 v90, v246, v247
	v_cvt_pk_bf16_f32 v91, v248, v249
	global_store_dwordx4 v1, v[84:87], s[8:9]
	global_store_dwordx4 v1, v[88:91], s[8:9] offset:1024
	s_add_u32 s8, s8, 0x800
	s_addc_u32 s9, s9, 0
	global_load_dwordx4 v[146:149], v1, s[6:7] nt
	global_load_dwordx4 v[150:153], v1, s[6:7] offset:1024 nt
	s_add_u32 s6, s6, 0x1800
	s_addc_u32 s7, s7, 0
	s_waitcnt vmcnt(14)
	v_lshlrev_b32_e32 v202, 16, v114
	v_and_b32_e32 v203, s14, v114
	v_lshlrev_b32_e32 v204, 16, v122
	v_and_b32_e32 v205, s14, v122
	v_pk_mul_f32 v[52:53], v[202:203], v[204:205]
	v_lshlrev_b32_e32 v206, 16, v115
	v_and_b32_e32 v207, s14, v115
	v_lshlrev_b32_e32 v208, 16, v123
	v_and_b32_e32 v209, s14, v123
	v_pk_mul_f32 v[54:55], v[206:207], v[208:209]
	v_lshlrev_b32_e32 v210, 16, v116
	v_and_b32_e32 v211, s14, v116
	v_lshlrev_b32_e32 v212, 16, v124
	v_and_b32_e32 v213, s14, v124
	v_pk_mul_f32 v[56:57], v[210:211], v[212:213]
	v_lshlrev_b32_e32 v202, 16, v117
	v_and_b32_e32 v203, s14, v117
	v_lshlrev_b32_e32 v204, 16, v125
	v_and_b32_e32 v205, s14, v125
	v_pk_mul_f32 v[58:59], v[202:203], v[204:205]
	v_lshlrev_b32_e32 v206, 16, v118
	v_and_b32_e32 v207, s14, v118
	v_lshlrev_b32_e32 v208, 16, v126
	v_and_b32_e32 v209, s14, v126
	v_pk_mul_f32 v[60:61], v[206:207], v[208:209]
	v_lshlrev_b32_e32 v210, 16, v119
	v_and_b32_e32 v211, s14, v119
	v_lshlrev_b32_e32 v212, 16, v127
	v_and_b32_e32 v213, s14, v127
	v_pk_mul_f32 v[62:63], v[210:211], v[212:213]
	v_lshlrev_b32_e32 v202, 16, v120
	v_and_b32_e32 v203, s14, v120
	v_lshlrev_b32_e32 v204, 16, v128
	v_and_b32_e32 v205, s14, v128
	v_pk_mul_f32 v[64:65], v[202:203], v[204:205]
	v_lshlrev_b32_e32 v206, 16, v121
	v_and_b32_e32 v207, s14, v121
	v_lshlrev_b32_e32 v208, 16, v129
	v_and_b32_e32 v209, s14, v129
	v_pk_mul_f32 v[66:67], v[206:207], v[208:209]
	global_load_dwordx4 v[114:117], v1, s[4:5] offset:2048 nt
	global_load_dwordx4 v[118:121], v1, s[4:5] offset:3072 nt
	global_load_dwordx4 v[122:125], v2, s[4:5] nt
	global_load_dwordx4 v[126:129], v2, s[4:5] offset:1024 nt
	s_add_u32 s4, s4, 0x1800
	s_addc_u32 s5, s5, 0
	s_add_i32 s12, s11, 1
	s_cmp_lt_u32 s12, 0x4000
	s_cselect_b32 s29, s3, s13
	s_and_b32 s27, s12, s29
	v_pk_mul_f32 v[234:235], v[20:21], v[98:99]
	v_pk_mul_f32 v[236:237], v[22:23], v[100:101]
	v_pk_mul_f32 v[238:239], v[24:25], v[102:103]
	v_pk_mul_f32 v[240:241], v[26:27], v[104:105]
	v_pk_mul_f32 v[242:243], v[28:29], v[106:107]
	v_pk_mul_f32 v[244:245], v[30:31], v[108:109]
	v_pk_mul_f32 v[246:247], v[32:33], v[110:111]
	v_pk_mul_f32 v[248:249], v[34:35], v[112:113]
	s_cmp_eq_u32 s27, 0
	s_cbranch_scc1 .Lcg9_np1
	v_pk_fma_f32 v[234:235], v[4:5], v[68:69], v[234:235]
	v_pk_fma_f32 v[236:237], v[6:7], v[70:71], v[236:237]
	v_pk_fma_f32 v[238:239], v[8:9], v[72:73], v[238:239]
	v_pk_fma_f32 v[240:241], v[10:11], v[74:75], v[240:241]
	v_pk_fma_f32 v[242:243], v[12:13], v[76:77], v[242:243]
	v_pk_fma_f32 v[244:245], v[14:15], v[78:79], v[244:245]
	v_pk_fma_f32 v[246:247], v[16:17], v[80:81], v[246:247]
	v_pk_fma_f32 v[248:249], v[18:19], v[82:83], v[248:249]

; __device__ __forceinline__ unsigned cvt_pk_bf16(float lo, float hi) { unsigned r; asm volatile("v_cvt_pk_bf16_f32 %0, %1, %2" : "=v"(r) : "v"(lo), "v"(hi)); return r; }
; __device__ __forceinline__ float bflo(unsigned w) { return __uint_as_float(w << 16); }
; __device__ __forceinline__ float bfhi(unsigned w) { return __uint_as_float(w & 0xffff0000u); }
; __device__ __forceinline__ void convgate_phase(const bf16_t* U, bf16_t* H, int rows, const float* ck, int gw, int NGW, int lane) {
;     ...
;             for (int e = 0; e < 4; ++e) {
;                 const f32x2 w0 = *(const f32x2*)(ck + c0 + 2 * e), w1 = *(const f32x2*)(ck + D + c0 + 2 * e), w2 = *(const f32x2*)(ck + 2 * D + c0 + 2 * e);
;                 const float lo = bflo(bq[hf][e]) * (w0[0] * (bflo(cp[hf][e]) * bflo(vp[hf][e])) + w1[0] * (bflo(cq[hf][e]) * bflo(vq[hf][e])) + w2[0] * (bflo(cn[hf][e]) * bflo(vn[hf][e])));
;                 const float hi = bfhi(bq[hf][e]) * (w0[1] * (bfhi(cp[hf][e]) * bfhi(vp[hf][e])) + w1[1] * (bfhi(cq[hf][e]) * bfhi(vq[hf][e])) + w2[1] * (bfhi(cn[hf][e]) * bfhi(vn[hf][e])));
;                 ow[e] = cvt_pk_bf16(lo, hi);
;             }
;             *(u32x4*)(H + (size_t)row * D + c0) = ow;
.Lcg9_nn1:
	v_lshlrev_b32_e32 v202, 16, v176
	v_and_b32_e32 v203, s14, v176
	v_pk_mul_f32 v[234:235], v[234:235], v[202:203]
	v_lshlrev_b32_e32 v206, 16, v177
	v_and_b32_e32 v207, s14, v177
	v_pk_mul_f32 v[236:237], v[236:237], v[206:207]
	v_lshlrev_b32_e32 v210, 16, v178
	v_and_b32_e32 v211, s14, v178
	v_pk_mul_f32 v[238:239], v[238:239], v[210:211]
	v_lshlrev_b32_e32 v202, 16, v179
	v_and_b32_e32 v203, s14, v179
	v_pk_mul_f32 v[240:241], v[240:241], v[202:203]
	v_lshlrev_b32_e32 v206, 16, v180
	v_and_b32_e32 v207, s14, v180
	v_pk_mul_f32 v[242:243], v[242:243], v[206:207]
	v_lshlrev_b32_e32 v210, 16, v181
	v_and_b32_e32 v211, s14, v181
	v_pk_mul_f32 v[244:245], v[244:245], v[210:211]
	v_lshlrev_b32_e32 v202, 16, v182
	v_and_b32_e32 v203, s14, v182
	v_pk_mul_f32 v[246:247], v[246:247], v[202:203]
	v_lshlrev_b32_e32 v206, 16, v183
	v_and_b32_e32 v207, s14, v183
	v_pk_mul_f32 v[248:249], v[248:249], v[206:207]
	v_cvt_pk_bf16_f32 v84, v234, v235
	v_cvt_pk_bf16_f32 v85, v236, v237
	v_cvt_pk_bf16_f32 v86, v238, v239
	v_cvt_pk_bf16_f32 v87, v240, v241
	v_cvt_pk_bf16_f32 v88, v242, v243
	v_cvt_pk_bf16_f32 v89, v244, v245
	v_cvt_pk_bf16_f32 v90, v246, v247
	v_cvt_pk_bf16_f32 v91, v248, v249
	global_store_dwordx4 v1, v[84:87], s[8:9]
	global_store_dwordx4 v1, v[88:91], s[8:9] offset:1024
	s_add_u32 s8, s8, 0x800
	s_addc_u32 s9, s9, 0
	global_load_dwordx4 v[176:179], v1, s[6:7] nt
	global_load_dwordx4 v[180:183], v1, s[6:7] offset:1024 nt
	s_add_u32 s6, s6, 0x1800
	s_addc_u32 s7, s7, 0
	s_waitcnt vmcnt(16)
	v_lshlrev_b32_e32 v202, 16, v130
	v_and_b32_e32 v203, s14, v130
	v_lshlrev_b32_e32 v204, 16, v138
	v_and_b32_e32 v205, s14, v138
	v_pk_mul_f32 v[68:69], v[202:203], v[204:205]
	v_lshlrev_b32_e32 v206, 16, v131
	v_and_b32_e32 v207, s14, v131
	v_lshlrev_b32_e32 v208, 16, v139
	v_and_b32_e32 v209, s14, v139
	v_pk_mul_f32 v[70:71], v[206:207], v[208:209]
	v_lshlrev_b32_e32 v210, 16, v132
	v_and_b32_e32 v211, s14, v132
	v_lshlrev_b32_e32 v212, 16, v140
	v_and_b32_e32 v213, s14, v140
	v_pk_mul_f32 v[72:73], v[210:211], v[212:213]
	v_lshlrev_b32_e32 v202, 16, v133
	v_and_b32_e32 v203, s14, v133
	v_lshlrev_b32_e32 v204, 16, v141
	v_and_b32_e32 v205, s14, v141
	v_pk_mul_f32 v[74:75], v[202:203], v[204:205]
	v_lshlrev_b32_e32 v206, 16, v134
	v_and_b32_e32 v207, s14, v134
	v_lshlrev_b32_e32 v208, 16, v142
	v_and_b32_e32 v209, s14, v142
	v_pk_mul_f32 v[76:77], v[206:207], v[208:209]
	v_lshlrev_b32_e32 v210, 16, v135
	v_and_b32_e32 v211, s14, v135
	v_lshlrev_b32_e32 v212, 16, v143
	v_and_b32_e32 v213, s14, v143
	v_pk_mul_f32 v[78:79], v[210:211], v[212:213]
	v_lshlrev_b32_e32 v202, 16, v136
	v_and_b32_e32 v203, s14, v136
	v_lshlrev_b32_e32 v204, 16, v144
	v_and_b32_e32 v205, s14, v144
	v_pk_mul_f32 v[80:81], v[202:203], v[204:205]
	v_lshlrev_b32_e32 v206, 16, v137
	v_and_b32_e32 v207, s14, v137
	v_lshlrev_b32_e32 v208, 16, v145
	v_and_b32_e32 v209, s14, v145
	v_pk_mul_f32 v[82:83], v[206:207], v[208:209]
	global_load_dwordx4 v[130:133], v1, s[4:5] offset:2048 nt
	global_load_dwordx4 v[134:137], v1, s[4:5] offset:3072 nt
	global_load_dwordx4 v[138:141], v2, s[4:5] nt
	global_load_dwordx4 v[142:145], v2, s[4:5] offset:1024 nt
	s_add_u32 s4, s4, 0x1800
	s_addc_u32 s5, s5, 0
	s_add_i32 s12, s11, 2
	s_cmp_lt_u32 s12, 0x4000
	s_cselect_b32 s29, s3, s13
	s_and_b32 s27, s12, s29
	v_pk_mul_f32 v[234:235], v[20:21], v[52:53]
	v_pk_mul_f32 v[236:237], v[22:23], v[54:55]
	v_pk_mul_f32 v[238:239], v[24:25], v[56:57]
	v_pk_mul_f32 v[240:241], v[26:27], v[58:59]
	v_pk_mul_f32 v[242:243], v[28:29], v[60:61]
	v_pk_mul_f32 v[244:245], v[30:31], v[62:63]
	v_pk_mul_f32 v[246:247], v[32:33], v[64:65]
	v_pk_mul_f32 v[248:249], v[34:35], v[66:67]
	s_cmp_eq_u32 s27, 0
	s_cbranch_scc1 .Lcg9_np2
	v_pk_fma_f32 v[234:235], v[4:5], v[98:99], v[234:235]
	v_pk_fma_f32 v[236:237], v[6:7], v[100:101], v[236:237]
	v_pk_fma_f32 v[238:239], v[8:9], v[102:103], v[238:239]
	v_pk_fma_f32 v[240:241], v[10:11], v[104:105], v[240:241]
	v_pk_fma_f32 v[242:243], v[12:13], v[106:107], v[242:243]
	v_pk_fma_f32 v[244:245], v[14:15], v[108:109], v[244:245]
	v_pk_fma_f32 v[246:247], v[16:17], v[110:111], v[246:247]
	v_pk_fma_f32 v[248:249], v[18:19], v[112:113], v[248:249]

; __device__ __forceinline__ unsigned cvt_pk_bf16(float lo, float hi) { unsigned r; asm volatile("v_cvt_pk_bf16_f32 %0, %1, %2" : "=v"(r) : "v"(lo), "v"(hi)); return r; }
; __device__ __forceinline__ float bflo(unsigned w) { return __uint_as_float(w << 16); }
; __device__ __forceinline__ float bfhi(unsigned w) { return __uint_as_float(w & 0xffff0000u); }
; __device__ __forceinline__ void convgate_phase(const bf16_t* U, bf16_t* H, int rows, const float* ck, int gw, int NGW, int lane) {
;     ...
;             for (int e = 0; e < 4; ++e) {
;                 const f32x2 w0 = *(const f32x2*)(ck + c0 + 2 * e), w1 = *(const f32x2*)(ck + D + c0 + 2 * e), w2 = *(const f32x2*)(ck + 2 * D + c0 + 2 * e);
;                 const float lo = bflo(bq[hf][e]) * (w0[0] * (bflo(cp[hf][e]) * bflo(vp[hf][e])) + w1[0] * (bflo(cq[hf][e]) * bflo(vq[hf][e])) + w2[0] * (bflo(cn[hf][e]) * bflo(vn[hf][e])));
;                 const float hi = bfhi(bq[hf][e]) * (w0[1] * (bfhi(cp[hf][e]) * bfhi(vp[hf][e])) + w1[1] * (bfhi(cq[hf][e]) * bfhi(vq[hf][e])) + w2[1] * (bfhi(cn[hf][e]) * bfhi(vn[hf][e])));
;                 ow[e] = cvt_pk_bf16(lo, hi);
;             }
;             *(u32x4*)(H + (size_t)row * D + c0) = ow;
.Lcg9_nn2:
	v_lshlrev_b32_e32 v202, 16, v226
	v_and_b32_e32 v203, s14, v226
	v_pk_mul_f32 v[234:235], v[234:235], v[202:203]
	v_lshlrev_b32_e32 v206, 16, v227
	v_and_b32_e32 v207, s14, v227
	v_pk_mul_f32 v[236:237], v[236:237], v[206:207]
	v_lshlrev_b32_e32 v210, 16, v228
	v_and_b32_e32 v211, s14, v228
	v_pk_mul_f32 v[238:239], v[238:239], v[210:211]
	v_lshlrev_b32_e32 v202, 16, v229
	v_and_b32_e32 v203, s14, v229
	v_pk_mul_f32 v[240:241], v[240:241], v[202:203]
	v_lshlrev_b32_e32 v206, 16, v230
	v_and_b32_e32 v207, s14, v230
	v_pk_mul_f32 v[242:243], v[242:243], v[206:207]
	v_lshlrev_b32_e32 v210, 16, v231
	v_and_b32_e32 v211, s14, v231
	v_pk_mul_f32 v[244:245], v[244:245], v[210:211]
	v_lshlrev_b32_e32 v202, 16, v232
	v_and_b32_e32 v203, s14, v232
	v_pk_mul_f32 v[246:247], v[246:247], v[202:203]
	v_lshlrev_b32_e32 v206, 16, v233
	v_and_b32_e32 v207, s14, v233
	v_pk_mul_f32 v[248:249], v[248:249], v[206:207]
	v_cvt_pk_bf16_f32 v84, v234, v235
	v_cvt_pk_bf16_f32 v85, v236, v237
	v_cvt_pk_bf16_f32 v86, v238, v239
	v_cvt_pk_bf16_f32 v87, v240, v241
	v_cvt_pk_bf16_f32 v88, v242, v243
	v_cvt_pk_bf16_f32 v89, v244, v245
	v_cvt_pk_bf16_f32 v90, v246, v247
	v_cvt_pk_bf16_f32 v91, v248, v249
	global_store_dwordx4 v1, v[84:87], s[8:9]
	global_store_dwordx4 v1, v[88:91], s[8:9] offset:1024
	s_add_u32 s8, s8, 0x800
	s_addc_u32 s9, s9, 0
	global_load_dwordx4 v[226:229], v1, s[6:7] nt
	global_load_dwordx4 v[230:233], v1, s[6:7] offset:1024 nt
	s_add_u32 s6, s6, 0x1800
	s_addc_u32 s7, s7, 0
	s_waitcnt vmcnt(16)
	v_lshlrev_b32_e32 v202, 16, v160
	v_and_b32_e32 v203, s14, v160
	v_lshlrev_b32_e32 v204, 16, v168
	v_and_b32_e32 v205, s14, v168
	v_pk_mul_f32 v[98:99], v[202:203], v[204:205]
	v_lshlrev_b32_e32 v206, 16, v161
	v_and_b32_e32 v207, s14, v161
	v_lshlrev_b32_e32 v208, 16, v169
	v_and_b32_e32 v209, s14, v169
	v_pk_mul_f32 v[100:101], v[206:207], v[208:209]
	v_lshlrev_b32_e32 v210, 16, v162
	v_and_b32_e32 v211, s14, v162
	v_lshlrev_b32_e32 v212, 16, v170
	v_and_b32_e32 v213, s14, v170
	v_pk_mul_f32 v[102:103], v[210:211], v[212:213]
	v_lshlrev_b32_e32 v202, 16, v163
	v_and_b32_e32 v203, s14, v163
	v_lshlrev_b32_e32 v204, 16, v171
	v_and_b32_e32 v205, s14, v171
	v_pk_mul_f32 v[104:105], v[202:203], v[204:205]
	v_lshlrev_b32_e32 v206, 16, v164
	v_and_b32_e32 v207, s14, v164
	v_lshlrev_b32_e32 v208, 16, v172
	v_and_b32_e32 v209, s14, v172
	v_pk_mul_f32 v[106:107], v[206:207], v[208:209]
	v_lshlrev_b32_e32 v210, 16, v165
	v_and_b32_e32 v211, s14, v165
	v_lshlrev_b32_e32 v212, 16, v173
	v_and_b32_e32 v213, s14, v173
	v_pk_mul_f32 v[108:109], v[210:211], v[212:213]
	v_lshlrev_b32_e32 v202, 16, v166
	v_and_b32_e32 v203, s14, v166
	v_lshlrev_b32_e32 v204, 16, v174
	v_and_b32_e32 v205, s14, v174
	v_pk_mul_f32 v[110:111], v[202:203], v[204:205]
	v_lshlrev_b32_e32 v206, 16, v167
	v_and_b32_e32 v207, s14, v167
	v_lshlrev_b32_e32 v208, 16, v175
	v_and_b32_e32 v209, s14, v175
	v_pk_mul_f32 v[112:113], v[206:207], v[208:209]
	global_load_dwordx4 v[160:163], v1, s[4:5] offset:2048 nt
	global_load_dwordx4 v[164:167], v1, s[4:5] offset:3072 nt
	global_load_dwordx4 v[168:171], v2, s[4:5] nt
	global_load_dwordx4 v[172:175], v2, s[4:5] offset:1024 nt
	s_add_u32 s4, s4, 0x1800
	s_addc_u32 s5, s5, 0
	s_add_i32 s12, s11, 3
	s_cmp_lt_u32 s12, 0x4000
	s_cselect_b32 s29, s3, s13
	s_and_b32 s27, s12, s29
	v_pk_mul_f32 v[234:235], v[20:21], v[68:69]
	v_pk_mul_f32 v[236:237], v[22:23], v[70:71]
	v_pk_mul_f32 v[238:239], v[24:25], v[72:73]
	v_pk_mul_f32 v[240:241], v[26:27], v[74:75]
	v_pk_mul_f32 v[242:243], v[28:29], v[76:77]
	v_pk_mul_f32 v[244:245], v[30:31], v[78:79]
	v_pk_mul_f32 v[246:247], v[32:33], v[80:81]
	v_pk_mul_f32 v[248:249], v[34:35], v[82:83]
	s_cmp_eq_u32 s27, 0
	s_cbranch_scc1 .Lcg9_np3
	v_pk_fma_f32 v[234:235], v[4:5], v[52:53], v[234:235]
	v_pk_fma_f32 v[236:237], v[6:7], v[54:55], v[236:237]
	v_pk_fma_f32 v[238:239], v[8:9], v[56:57], v[238:239]
	v_pk_fma_f32 v[240:241], v[10:11], v[58:59], v[240:241]
	v_pk_fma_f32 v[242:243], v[12:13], v[60:61], v[242:243]
	v_pk_fma_f32 v[244:245], v[14:15], v[62:63], v[244:245]
	v_pk_fma_f32 v[246:247], v[16:17], v[64:65], v[246:247]
	v_pk_fma_f32 v[248:249], v[18:19], v[66:67], v[248:249]

; __device__ __forceinline__ unsigned cvt_pk_bf16(float lo, float hi) { unsigned r; asm volatile("v_cvt_pk_bf16_f32 %0, %1, %2" : "=v"(r) : "v"(lo), "v"(hi)); return r; }
; __device__ __forceinline__ float bflo(unsigned w) { return __uint_as_float(w << 16); }
; __device__ __forceinline__ float bfhi(unsigned w) { return __uint_as_float(w & 0xffff0000u); }
; __device__ __forceinline__ void convgate_phase(const bf16_t* U, bf16_t* H, int rows, const float* ck, int gw, int NGW, int lane) {
;     ...
;             for (int e = 0; e < 4; ++e) {
;                 const f32x2 w0 = *(const f32x2*)(ck + c0 + 2 * e), w1 = *(const f32x2*)(ck + D + c0 + 2 * e), w2 = *(const f32x2*)(ck + 2 * D + c0 + 2 * e);
;                 const float lo = bflo(bq[hf][e]) * (w0[0] * (bflo(cp[hf][e]) * bflo(vp[hf][e])) + w1[0] * (bflo(cq[hf][e]) * bflo(vq[hf][e])) + w2[0] * (bflo(cn[hf][e]) * bflo(vn[hf][e])));
;                 const float hi = bfhi(bq[hf][e]) * (w0[1] * (bfhi(cp[hf][e]) * bfhi(vp[hf][e])) + w1[1] * (bfhi(cq[hf][e]) * bfhi(vq[hf][e])) + w2[1] * (bfhi(cn[hf][e]) * bfhi(vn[hf][e])));
;                 ow[e] = cvt_pk_bf16(lo, hi);
;             }
;             *(u32x4*)(H + (size_t)row * D + c0) = ow;
.Lcg9_nn3:
	v_lshlrev_b32_e32 v202, 16, v146
	v_and_b32_e32 v203, s14, v146
	v_pk_mul_f32 v[234:235], v[234:235], v[202:203]
	v_lshlrev_b32_e32 v206, 16, v147
	v_and_b32_e32 v207, s14, v147
	v_pk_mul_f32 v[236:237], v[236:237], v[206:207]
	v_lshlrev_b32_e32 v210, 16, v148
	v_and_b32_e32 v211, s14, v148
	v_pk_mul_f32 v[238:239], v[238:239], v[210:211]
	v_lshlrev_b32_e32 v202, 16, v149
	v_and_b32_e32 v203, s14, v149
	v_pk_mul_f32 v[240:241], v[240:241], v[202:203]
	v_lshlrev_b32_e32 v206, 16, v150
	v_and_b32_e32 v207, s14, v150
	v_pk_mul_f32 v[242:243], v[242:243], v[206:207]
	v_lshlrev_b32_e32 v210, 16, v151
	v_and_b32_e32 v211, s14, v151
	v_pk_mul_f32 v[244:245], v[244:245], v[210:211]
	v_lshlrev_b32_e32 v202, 16, v152
	v_and_b32_e32 v203, s14, v152
	v_pk_mul_f32 v[246:247], v[246:247], v[202:203]
	v_lshlrev_b32_e32 v206, 16, v153
	v_and_b32_e32 v207, s14, v153
	v_pk_mul_f32 v[248:249], v[248:249], v[206:207]
	v_cvt_pk_bf16_f32 v84, v234, v235
	v_cvt_pk_bf16_f32 v85, v236, v237
	v_cvt_pk_bf16_f32 v86, v238, v239
	v_cvt_pk_bf16_f32 v87, v240, v241
	v_cvt_pk_bf16_f32 v88, v242, v243
	v_cvt_pk_bf16_f32 v89, v244, v245
	v_cvt_pk_bf16_f32 v90, v246, v247
	v_cvt_pk_bf16_f32 v91, v248, v249
	global_store_dwordx4 v1, v[84:87], s[8:9]
	global_store_dwordx4 v1, v[88:91], s[8:9] offset:1024
	s_add_u32 s8, s8, 0x800
	s_addc_u32 s9, s9, 0
	global_load_dwordx4 v[146:149], v1, s[6:7] nt
	global_load_dwordx4 v[150:153], v1, s[6:7] offset:1024 nt
	s_add_u32 s6, s6, 0x1800
	s_addc_u32 s7, s7, 0
	s_waitcnt vmcnt(16)
	v_lshlrev_b32_e32 v202, 16, v114
	v_and_b32_e32 v203, s14, v114
	v_lshlrev_b32_e32 v204, 16, v122
	v_and_b32_e32 v205, s14, v122
	v_pk_mul_f32 v[52:53], v[202:203], v[204:205]
	v_lshlrev_b32_e32 v206, 16, v115
	v_and_b32_e32 v207, s14, v115
	v_lshlrev_b32_e32 v208, 16, v123
	v_and_b32_e32 v209, s14, v123
	v_pk_mul_f32 v[54:55], v[206:207], v[208:209]
	v_lshlrev_b32_e32 v210, 16, v116
	v_and_b32_e32 v211, s14, v116
	v_lshlrev_b32_e32 v212, 16, v124
	v_and_b32_e32 v213, s14, v124
	v_pk_mul_f32 v[56:57], v[210:211], v[212:213]
	v_lshlrev_b32_e32 v202, 16, v117
	v_and_b32_e32 v203, s14, v117
	v_lshlrev_b32_e32 v204, 16, v125
	v_and_b32_e32 v205, s14, v125
	v_pk_mul_f32 v[58:59], v[202:203], v[204:205]
	v_lshlrev_b32_e32 v206, 16, v118
	v_and_b32_e32 v207, s14, v118
	v_lshlrev_b32_e32 v208, 16, v126
	v_and_b32_e32 v209, s14, v126
	v_pk_mul_f32 v[60:61], v[206:207], v[208:209]
	v_lshlrev_b32_e32 v210, 16, v119
	v_and_b32_e32 v211, s14, v119
	v_lshlrev_b32_e32 v212, 16, v127
	v_and_b32_e32 v213, s14, v127
	v_pk_mul_f32 v[62:63], v[210:211], v[212:213]
	v_lshlrev_b32_e32 v202, 16, v120
	v_and_b32_e32 v203, s14, v120
	v_lshlrev_b32_e32 v204, 16, v128
	v_and_b32_e32 v205, s14, v128
	v_pk_mul_f32 v[64:65], v[202:203], v[204:205]
	v_lshlrev_b32_e32 v206, 16, v121
	v_and_b32_e32 v207, s14, v121
	v_lshlrev_b32_e32 v208, 16, v129
	v_and_b32_e32 v209, s14, v129
	v_pk_mul_f32 v[66:67], v[206:207], v[208:209]
	global_load_dwordx4 v[114:117], v1, s[4:5] offset:2048 nt
	global_load_dwordx4 v[118:121], v1, s[4:5] offset:3072 nt
	global_load_dwordx4 v[122:125], v2, s[4:5] nt
	global_load_dwordx4 v[126:129], v2, s[4:5] offset:1024 nt
	s_add_u32 s4, s4, 0x1800
	s_addc_u32 s5, s5, 0
	s_add_i32 s12, s11, 4
	s_cmp_lt_u32 s12, 0x4000
	s_cselect_b32 s29, s3, s13
	s_and_b32 s27, s12, s29
	v_pk_mul_f32 v[234:235], v[20:21], v[98:99]
	v_pk_mul_f32 v[236:237], v[22:23], v[100:101]
	v_pk_mul_f32 v[238:239], v[24:25], v[102:103]
	v_pk_mul_f32 v[240:241], v[26:27], v[104:105]
	v_pk_mul_f32 v[242:243], v[28:29], v[106:107]
	v_pk_mul_f32 v[244:245], v[30:31], v[108:109]
	v_pk_mul_f32 v[246:247], v[32:33], v[110:111]
	v_pk_mul_f32 v[248:249], v[34:35], v[112:113]
	s_cmp_eq_u32 s27, 0
	s_cbranch_scc1 .Lcg9_np4
	v_pk_fma_f32 v[234:235], v[4:5], v[68:69], v[234:235]
	v_pk_fma_f32 v[236:237], v[6:7], v[70:71], v[236:237]
	v_pk_fma_f32 v[238:239], v[8:9], v[72:73], v[238:239]
	v_pk_fma_f32 v[240:241], v[10:11], v[74:75], v[240:241]
	v_pk_fma_f32 v[242:243], v[12:13], v[76:77], v[242:243]
	v_pk_fma_f32 v[244:245], v[14:15], v[78:79], v[244:245]
	v_pk_fma_f32 v[246:247], v[16:17], v[80:81], v[246:247]
	v_pk_fma_f32 v[248:249], v[18:19], v[82:83], v[248:249]

; __device__ __forceinline__ unsigned cvt_pk_bf16(float lo, float hi) { unsigned r; asm volatile("v_cvt_pk_bf16_f32 %0, %1, %2" : "=v"(r) : "v"(lo), "v"(hi)); return r; }
; __device__ __forceinline__ float bflo(unsigned w) { return __uint_as_float(w << 16); }
; __device__ __forceinline__ float bfhi(unsigned w) { return __uint_as_float(w & 0xffff0000u); }
; __device__ __forceinline__ void convgate_phase(const bf16_t* U, bf16_t* H, int rows, const float* ck, int gw, int NGW, int lane) {
;     ...
;             for (int e = 0; e < 4; ++e) {
;                 const f32x2 w0 = *(const f32x2*)(ck + c0 + 2 * e), w1 = *(const f32x2*)(ck + D + c0 + 2 * e), w2 = *(const f32x2*)(ck + 2 * D + c0 + 2 * e);
;                 const float lo = bflo(bq[hf][e]) * (w0[0] * (bflo(cp[hf][e]) * bflo(vp[hf][e])) + w1[0] * (bflo(cq[hf][e]) * bflo(vq[hf][e])) + w2[0] * (bflo(cn[hf][e]) * bflo(vn[hf][e])));
;                 const float hi = bfhi(bq[hf][e]) * (w0[1] * (bfhi(cp[hf][e]) * bfhi(vp[hf][e])) + w1[1] * (bfhi(cq[hf][e]) * bfhi(vq[hf][e])) + w2[1] * (bfhi(cn[hf][e]) * bfhi(vn[hf][e])));
;                 ow[e] = cvt_pk_bf16(lo, hi);
;             }
;             *(u32x4*)(H + (size_t)row * D + c0) = ow;
.Lcg9_nn4:
	v_lshlrev_b32_e32 v202, 16, v176
	v_and_b32_e32 v203, s14, v176
	v_pk_mul_f32 v[234:235], v[234:235], v[202:203]
	v_lshlrev_b32_e32 v206, 16, v177
	v_and_b32_e32 v207, s14, v177
	v_pk_mul_f32 v[236:237], v[236:237], v[206:207]
	v_lshlrev_b32_e32 v210, 16, v178
	v_and_b32_e32 v211, s14, v178
	v_pk_mul_f32 v[238:239], v[238:239], v[210:211]
	v_lshlrev_b32_e32 v202, 16, v179
	v_and_b32_e32 v203, s14, v179
	v_pk_mul_f32 v[240:241], v[240:241], v[202:203]
	v_lshlrev_b32_e32 v206, 16, v180
	v_and_b32_e32 v207, s14, v180
	v_pk_mul_f32 v[242:243], v[242:243], v[206:207]
	v_lshlrev_b32_e32 v210, 16, v181
	v_and_b32_e32 v211, s14, v181
	v_pk_mul_f32 v[244:245], v[244:245], v[210:211]
	v_lshlrev_b32_e32 v202, 16, v182
	v_and_b32_e32 v203, s14, v182
	v_pk_mul_f32 v[246:247], v[246:247], v[202:203]
	v_lshlrev_b32_e32 v206, 16, v183
	v_and_b32_e32 v207, s14, v183
	v_pk_mul_f32 v[248:249], v[248:249], v[206:207]
	v_cvt_pk_bf16_f32 v84, v234, v235
	v_cvt_pk_bf16_f32 v85, v236, v237
	v_cvt_pk_bf16_f32 v86, v238, v239
	v_cvt_pk_bf16_f32 v87, v240, v241
	v_cvt_pk_bf16_f32 v88, v242, v243
	v_cvt_pk_bf16_f32 v89, v244, v245
	v_cvt_pk_bf16_f32 v90, v246, v247
	v_cvt_pk_bf16_f32 v91, v248, v249
	global_store_dwordx4 v1, v[84:87], s[8:9]
	global_store_dwordx4 v1, v[88:91], s[8:9] offset:1024
	s_add_u32 s8, s8, 0x800
	s_addc_u32 s9, s9, 0
	global_load_dwordx4 v[176:179], v1, s[6:7] nt
	global_load_dwordx4 v[180:183], v1, s[6:7] offset:1024 nt
	s_add_u32 s6, s6, 0x1800
	s_addc_u32 s7, s7, 0
	s_waitcnt vmcnt(16)
	v_lshlrev_b32_e32 v202, 16, v130
	v_and_b32_e32 v203, s14, v130
	v_lshlrev_b32_e32 v204, 16, v138
	v_and_b32_e32 v205, s14, v138
	v_pk_mul_f32 v[68:69], v[202:203], v[204:205]
	v_lshlrev_b32_e32 v206, 16, v131
	v_and_b32_e32 v207, s14, v131
	v_lshlrev_b32_e32 v208, 16, v139
	v_and_b32_e32 v209, s14, v139
	v_pk_mul_f32 v[70:71], v[206:207], v[208:209]
	v_lshlrev_b32_e32 v210, 16, v132
	v_and_b32_e32 v211, s14, v132
	v_lshlrev_b32_e32 v212, 16, v140
	v_and_b32_e32 v213, s14, v140
	v_pk_mul_f32 v[72:73], v[210:211], v[212:213]
	v_lshlrev_b32_e32 v202, 16, v133
	v_and_b32_e32 v203, s14, v133
	v_lshlrev_b32_e32 v204, 16, v141
	v_and_b32_e32 v205, s14, v141
	v_pk_mul_f32 v[74:75], v[202:203], v[204:205]
	v_lshlrev_b32_e32 v206, 16, v134
	v_and_b32_e32 v207, s14, v134
	v_lshlrev_b32_e32 v208, 16, v142
	v_and_b32_e32 v209, s14, v142
	v_pk_mul_f32 v[76:77], v[206:207], v[208:209]
	v_lshlrev_b32_e32 v210, 16, v135
	v_and_b32_e32 v211, s14, v135
	v_lshlrev_b32_e32 v212, 16, v143
	v_and_b32_e32 v213, s14, v143
	v_pk_mul_f32 v[78:79], v[210:211], v[212:213]
	v_lshlrev_b32_e32 v202, 16, v136
	v_and_b32_e32 v203, s14, v136
	v_lshlrev_b32_e32 v204, 16, v144
	v_and_b32_e32 v205, s14, v144
	v_pk_mul_f32 v[80:81], v[202:203], v[204:205]
	v_lshlrev_b32_e32 v206, 16, v137
	v_and_b32_e32 v207, s14, v137
	v_lshlrev_b32_e32 v208, 16, v145
	v_and_b32_e32 v209, s14, v145
	v_pk_mul_f32 v[82:83], v[206:207], v[208:209]
	global_load_dwordx4 v[130:133], v1, s[4:5] offset:2048 nt
	global_load_dwordx4 v[134:137], v1, s[4:5] offset:3072 nt
	global_load_dwordx4 v[138:141], v2, s[4:5] nt
	global_load_dwordx4 v[142:145], v2, s[4:5] offset:1024 nt
	s_add_u32 s4, s4, 0x1800
	s_addc_u32 s5, s5, 0
	s_add_i32 s12, s11, 5
	s_cmp_lt_u32 s12, 0x4000
	s_cselect_b32 s29, s3, s13
	s_and_b32 s27, s12, s29
	v_pk_mul_f32 v[234:235], v[20:21], v[52:53]
	v_pk_mul_f32 v[236:237], v[22:23], v[54:55]
	v_pk_mul_f32 v[238:239], v[24:25], v[56:57]
	v_pk_mul_f32 v[240:241], v[26:27], v[58:59]
	v_pk_mul_f32 v[242:243], v[28:29], v[60:61]
	v_pk_mul_f32 v[244:245], v[30:31], v[62:63]
	v_pk_mul_f32 v[246:247], v[32:33], v[64:65]
	v_pk_mul_f32 v[248:249], v[34:35], v[66:67]
	s_cmp_eq_u32 s27, 0
	s_cbranch_scc1 .Lcg9_np5
	v_pk_fma_f32 v[234:235], v[4:5], v[98:99], v[234:235]
	v_pk_fma_f32 v[236:237], v[6:7], v[100:101], v[236:237]
	v_pk_fma_f32 v[238:239], v[8:9], v[102:103], v[238:239]
	v_pk_fma_f32 v[240:241], v[10:11], v[104:105], v[240:241]
	v_pk_fma_f32 v[242:243], v[12:13], v[106:107], v[242:243]
	v_pk_fma_f32 v[244:245], v[14:15], v[108:109], v[244:245]
	v_pk_fma_f32 v[246:247], v[16:17], v[110:111], v[246:247]
	v_pk_fma_f32 v[248:249], v[18:19], v[112:113], v[248:249]

; __device__ __forceinline__ unsigned cvt_pk_bf16(float lo, float hi) { unsigned r; asm volatile("v_cvt_pk_bf16_f32 %0, %1, %2" : "=v"(r) : "v"(lo), "v"(hi)); return r; }
; __device__ __forceinline__ float bflo(unsigned w) { return __uint_as_float(w << 16); }
; __device__ __forceinline__ float bfhi(unsigned w) { return __uint_as_float(w & 0xffff0000u); }
; __device__ __forceinline__ void convgate_phase(const bf16_t* U, bf16_t* H, int rows, const float* ck, int gw, int NGW, int lane) {
;     ...
;             for (int e = 0; e < 4; ++e) {
;                 const f32x2 w0 = *(const f32x2*)(ck + c0 + 2 * e), w1 = *(const f32x2*)(ck + D + c0 + 2 * e), w2 = *(const f32x2*)(ck + 2 * D + c0 + 2 * e);
;                 const float lo = bflo(bq[hf][e]) * (w0[0] * (bflo(cp[hf][e]) * bflo(vp[hf][e])) + w1[0] * (bflo(cq[hf][e]) * bflo(vq[hf][e])) + w2[0] * (bflo(cn[hf][e]) * bflo(vn[hf][e])));
;                 const float hi = bfhi(bq[hf][e]) * (w0[1] * (bfhi(cp[hf][e]) * bfhi(vp[hf][e])) + w1[1] * (bfhi(cq[hf][e]) * bfhi(vq[hf][e])) + w2[1] * (bfhi(cn[hf][e]) * bfhi(vn[hf][e])));
;                 ow[e] = cvt_pk_bf16(lo, hi);
;             }
;             *(u32x4*)(H + (size_t)row * D + c0) = ow;
.Lcg9_nn5:
	v_lshlrev_b32_e32 v202, 16, v226
	v_and_b32_e32 v203, s14, v226
	v_pk_mul_f32 v[234:235], v[234:235], v[202:203]
	v_lshlrev_b32_e32 v206, 16, v227
	v_and_b32_e32 v207, s14, v227
	v_pk_mul_f32 v[236:237], v[236:237], v[206:207]
	v_lshlrev_b32_e32 v210, 16, v228
	v_and_b32_e32 v211, s14, v228
	v_pk_mul_f32 v[238:239], v[238:239], v[210:211]
	v_lshlrev_b32_e32 v202, 16, v229
	v_and_b32_e32 v203, s14, v229
	v_pk_mul_f32 v[240:241], v[240:241], v[202:203]
	v_lshlrev_b32_e32 v206, 16, v230
	v_and_b32_e32 v207, s14, v230
	v_pk_mul_f32 v[242:243], v[242:243], v[206:207]
	v_lshlrev_b32_e32 v210, 16, v231
	v_and_b32_e32 v211, s14, v231
	v_pk_mul_f32 v[244:245], v[244:245], v[210:211]
	v_lshlrev_b32_e32 v202, 16, v232
	v_and_b32_e32 v203, s14, v232
	v_pk_mul_f32 v[246:247], v[246:247], v[202:203]
	v_lshlrev_b32_e32 v206, 16, v233
	v_and_b32_e32 v207, s14, v233
	v_pk_mul_f32 v[248:249], v[248:249], v[206:207]
	v_cvt_pk_bf16_f32 v84, v234, v235
	v_cvt_pk_bf16_f32 v85, v236, v237
	v_cvt_pk_bf16_f32 v86, v238, v239
	v_cvt_pk_bf16_f32 v87, v240, v241
	v_cvt_pk_bf16_f32 v88, v242, v243
	v_cvt_pk_bf16_f32 v89, v244, v245
	v_cvt_pk_bf16_f32 v90, v246, v247
	v_cvt_pk_bf16_f32 v91, v248, v249
	global_store_dwordx4 v1, v[84:87], s[8:9]
	global_store_dwordx4 v1, v[88:91], s[8:9] offset:1024
	s_add_u32 s8, s8, 0x800
	s_addc_u32 s9, s9, 0
	global_load_dwordx4 v[226:229], v1, s[6:7] nt
	global_load_dwordx4 v[230:233], v1, s[6:7] offset:1024 nt
	s_add_u32 s6, s6, 0x1800
	s_addc_u32 s7, s7, 0
	s_waitcnt vmcnt(16)
	v_lshlrev_b32_e32 v202, 16, v160
	v_and_b32_e32 v203, s14, v160
	v_lshlrev_b32_e32 v204, 16, v168
	v_and_b32_e32 v205, s14, v168
	v_pk_mul_f32 v[98:99], v[202:203], v[204:205]
	v_lshlrev_b32_e32 v206, 16, v161
	v_and_b32_e32 v207, s14, v161
	v_lshlrev_b32_e32 v208, 16, v169
	v_and_b32_e32 v209, s14, v169
	v_pk_mul_f32 v[100:101], v[206:207], v[208:209]
	v_lshlrev_b32_e32 v210, 16, v162
	v_and_b32_e32 v211, s14, v162
	v_lshlrev_b32_e32 v212, 16, v170
	v_and_b32_e32 v213, s14, v170
	v_pk_mul_f32 v[102:103], v[210:211], v[212:213]
	v_lshlrev_b32_e32 v202, 16, v163
	v_and_b32_e32 v203, s14, v163
	v_lshlrev_b32_e32 v204, 16, v171
	v_and_b32_e32 v205, s14, v171
	v_pk_mul_f32 v[104:105], v[202:203], v[204:205]
	v_lshlrev_b32_e32 v206, 16, v164
	v_and_b32_e32 v207, s14, v164
	v_lshlrev_b32_e32 v208, 16, v172
	v_and_b32_e32 v209, s14, v172
	v_pk_mul_f32 v[106:107], v[206:207], v[208:209]
	v_lshlrev_b32_e32 v210, 16, v165
	v_and_b32_e32 v211, s14, v165
	v_lshlrev_b32_e32 v212, 16, v173
	v_and_b32_e32 v213, s14, v173
	v_pk_mul_f32 v[108:109], v[210:211], v[212:213]
	v_lshlrev_b32_e32 v202, 16, v166
	v_and_b32_e32 v203, s14, v166
	v_lshlrev_b32_e32 v204, 16, v174
	v_and_b32_e32 v205, s14, v174
	v_pk_mul_f32 v[110:111], v[202:203], v[204:205]
	v_lshlrev_b32_e32 v206, 16, v167
	v_and_b32_e32 v207, s14, v167
	v_lshlrev_b32_e32 v208, 16, v175
	v_and_b32_e32 v209, s14, v175
	v_pk_mul_f32 v[112:113], v[206:207], v[208:209]
	s_add_i32 s12, s11, 6
	s_cmp_lt_u32 s12, 0x4000
	s_cselect_b32 s29, s3, s13
	s_and_b32 s27, s12, s29
	v_pk_mul_f32 v[234:235], v[20:21], v[68:69]
	v_pk_mul_f32 v[236:237], v[22:23], v[70:71]
	v_pk_mul_f32 v[238:239], v[24:25], v[72:73]
	v_pk_mul_f32 v[240:241], v[26:27], v[74:75]
	v_pk_mul_f32 v[242:243], v[28:29], v[76:77]
	v_pk_mul_f32 v[244:245], v[30:31], v[78:79]
	v_pk_mul_f32 v[246:247], v[32:33], v[80:81]
	v_pk_mul_f32 v[248:249], v[34:35], v[82:83]
	s_cmp_eq_u32 s27, 0
	s_cbranch_scc1 .Lcg9_np6
	v_pk_fma_f32 v[234:235], v[4:5], v[52:53], v[234:235]
	v_pk_fma_f32 v[236:237], v[6:7], v[54:55], v[236:237]
	v_pk_fma_f32 v[238:239], v[8:9], v[56:57], v[238:239]
	v_pk_fma_f32 v[240:241], v[10:11], v[58:59], v[240:241]
	v_pk_fma_f32 v[242:243], v[12:13], v[60:61], v[242:243]
	v_pk_fma_f32 v[244:245], v[14:15], v[62:63], v[244:245]
	v_pk_fma_f32 v[246:247], v[16:17], v[64:65], v[246:247]
	v_pk_fma_f32 v[248:249], v[18:19], v[66:67], v[248:249]

; __device__ __forceinline__ unsigned cvt_pk_bf16(float lo, float hi) { unsigned r; asm volatile("v_cvt_pk_bf16_f32 %0, %1, %2" : "=v"(r) : "v"(lo), "v"(hi)); return r; }
; __device__ __forceinline__ float bflo(unsigned w) { return __uint_as_float(w << 16); }
; __device__ __forceinline__ float bfhi(unsigned w) { return __uint_as_float(w & 0xffff0000u); }
; __device__ __forceinline__ void convgate_phase(const bf16_t* U, bf16_t* H, int rows, const float* ck, int gw, int NGW, int lane) {
;     ...
;             for (int e = 0; e < 4; ++e) {
;                 const f32x2 w0 = *(const f32x2*)(ck + c0 + 2 * e), w1 = *(const f32x2*)(ck + D + c0 + 2 * e), w2 = *(const f32x2*)(ck + 2 * D + c0 + 2 * e);
;                 const float lo = bflo(bq[hf][e]) * (w0[0] * (bflo(cp[hf][e]) * bflo(vp[hf][e])) + w1[0] * (bflo(cq[hf][e]) * bflo(vq[hf][e])) + w2[0] * (bflo(cn[hf][e]) * bflo(vn[hf][e])));
;                 const float hi = bfhi(bq[hf][e]) * (w0[1] * (bfhi(cp[hf][e]) * bfhi(vp[hf][e])) + w1[1] * (bfhi(cq[hf][e]) * bfhi(vq[hf][e])) + w2[1] * (bfhi(cn[hf][e]) * bfhi(vn[hf][e])));
;                 ow[e] = cvt_pk_bf16(lo, hi);
;             }
;             *(u32x4*)(H + (size_t)row * D + c0) = ow;
.Lcg9_nn6:
	v_lshlrev_b32_e32 v202, 16, v146
	v_and_b32_e32 v203, s14, v146
	v_pk_mul_f32 v[234:235], v[234:235], v[202:203]
	v_lshlrev_b32_e32 v206, 16, v147
	v_and_b32_e32 v207, s14, v147
	v_pk_mul_f32 v[236:237], v[236:237], v[206:207]
	v_lshlrev_b32_e32 v210, 16, v148
	v_and_b32_e32 v211, s14, v148
	v_pk_mul_f32 v[238:239], v[238:239], v[210:211]
	v_lshlrev_b32_e32 v202, 16, v149
	v_and_b32_e32 v203, s14, v149
	v_pk_mul_f32 v[240:241], v[240:241], v[202:203]
	v_lshlrev_b32_e32 v206, 16, v150
	v_and_b32_e32 v207, s14, v150
	v_pk_mul_f32 v[242:243], v[242:243], v[206:207]
	v_lshlrev_b32_e32 v210, 16, v151
	v_and_b32_e32 v211, s14, v151
	v_pk_mul_f32 v[244:245], v[244:245], v[210:211]
	v_lshlrev_b32_e32 v202, 16, v152
	v_and_b32_e32 v203, s14, v152
	v_pk_mul_f32 v[246:247], v[246:247], v[202:203]
	v_lshlrev_b32_e32 v206, 16, v153
	v_and_b32_e32 v207, s14, v153
	v_pk_mul_f32 v[248:249], v[248:249], v[206:207]
	v_cvt_pk_bf16_f32 v84, v234, v235
	v_cvt_pk_bf16_f32 v85, v236, v237
	v_cvt_pk_bf16_f32 v86, v238, v239
	v_cvt_pk_bf16_f32 v87, v240, v241
	v_cvt_pk_bf16_f32 v88, v242, v243
	v_cvt_pk_bf16_f32 v89, v244, v245
	v_cvt_pk_bf16_f32 v90, v246, v247
	v_cvt_pk_bf16_f32 v91, v248, v249
	global_store_dwordx4 v1, v[84:87], s[8:9]
	global_store_dwordx4 v1, v[88:91], s[8:9] offset:1024
	s_add_u32 s8, s8, 0x800
	s_addc_u32 s9, s9, 0
	s_waitcnt vmcnt(10)
	v_lshlrev_b32_e32 v202, 16, v114
	v_and_b32_e32 v203, s14, v114
	v_lshlrev_b32_e32 v204, 16, v122
	v_and_b32_e32 v205, s14, v122
	v_pk_mul_f32 v[52:53], v[202:203], v[204:205]
	v_lshlrev_b32_e32 v206, 16, v115
	v_and_b32_e32 v207, s14, v115
	v_lshlrev_b32_e32 v208, 16, v123
	v_and_b32_e32 v209, s14, v123
	v_pk_mul_f32 v[54:55], v[206:207], v[208:209]
	v_lshlrev_b32_e32 v210, 16, v116
	v_and_b32_e32 v211, s14, v116
	v_lshlrev_b32_e32 v212, 16, v124
	v_and_b32_e32 v213, s14, v124
	v_pk_mul_f32 v[56:57], v[210:211], v[212:213]
	v_lshlrev_b32_e32 v202, 16, v117
	v_and_b32_e32 v203, s14, v117
	v_lshlrev_b32_e32 v204, 16, v125
	v_and_b32_e32 v205, s14, v125
	v_pk_mul_f32 v[58:59], v[202:203], v[204:205]
	v_lshlrev_b32_e32 v206, 16, v118
	v_and_b32_e32 v207, s14, v118
	v_lshlrev_b32_e32 v208, 16, v126
	v_and_b32_e32 v209, s14, v126
	v_pk_mul_f32 v[60:61], v[206:207], v[208:209]
	v_lshlrev_b32_e32 v210, 16, v119
	v_and_b32_e32 v211, s14, v119
	v_lshlrev_b32_e32 v212, 16, v127
	v_and_b32_e32 v213, s14, v127
	v_pk_mul_f32 v[62:63], v[210:211], v[212:213]
	v_lshlrev_b32_e32 v202, 16, v120
	v_and_b32_e32 v203, s14, v120
	v_lshlrev_b32_e32 v204, 16, v128
	v_and_b32_e32 v205, s14, v128
	v_pk_mul_f32 v[64:65], v[202:203], v[204:205]
	v_lshlrev_b32_e32 v206, 16, v121
	v_and_b32_e32 v207, s14, v121
	v_lshlrev_b32_e32 v208, 16, v129
	v_and_b32_e32 v209, s14, v129
	v_pk_mul_f32 v[66:67], v[206:207], v[208:209]
	s_add_i32 s12, s11, 7
	s_cmp_lt_u32 s12, 0x4000
	s_cselect_b32 s29, s3, s13
	s_and_b32 s27, s12, s29
	v_pk_mul_f32 v[234:235], v[20:21], v[98:99]
	v_pk_mul_f32 v[236:237], v[22:23], v[100:101]
	v_pk_mul_f32 v[238:239], v[24:25], v[102:103]
	v_pk_mul_f32 v[240:241], v[26:27], v[104:105]
	v_pk_mul_f32 v[242:243], v[28:29], v[106:107]
	v_pk_mul_f32 v[244:245], v[30:31], v[108:109]
	v_pk_mul_f32 v[246:247], v[32:33], v[110:111]
	v_pk_mul_f32 v[248:249], v[34:35], v[112:113]
	s_cmp_eq_u32 s27, 0
	s_cbranch_scc1 .Lcg9_np7
	v_pk_fma_f32 v[234:235], v[4:5], v[68:69], v[234:235]
	v_pk_fma_f32 v[236:237], v[6:7], v[70:71], v[236:237]
	v_pk_fma_f32 v[238:239], v[8:9], v[72:73], v[238:239]
	v_pk_fma_f32 v[240:241], v[10:11], v[74:75], v[240:241]
	v_pk_fma_f32 v[242:243], v[12:13], v[76:77], v[242:243]
	v_pk_fma_f32 v[244:245], v[14:15], v[78:79], v[244:245]
	v_pk_fma_f32 v[246:247], v[16:17], v[80:81], v[246:247]
	v_pk_fma_f32 v[248:249], v[18:19], v[82:83], v[248:249]

; __device__ __forceinline__ unsigned cvt_pk_bf16(float lo, float hi) { unsigned r; asm volatile("v_cvt_pk_bf16_f32 %0, %1, %2" : "=v"(r) : "v"(lo), "v"(hi)); return r; }
; __device__ __forceinline__ float bflo(unsigned w) { return __uint_as_float(w << 16); }
; __device__ __forceinline__ float bfhi(unsigned w) { return __uint_as_float(w & 0xffff0000u); }
; __device__ __forceinline__ void convgate_phase(const bf16_t* U, bf16_t* H, int rows, const float* ck, int gw, int NGW, int lane) {
;     ...
;             for (int e = 0; e < 4; ++e) {
;                 const f32x2 w0 = *(const f32x2*)(ck + c0 + 2 * e), w1 = *(const f32x2*)(ck + D + c0 + 2 * e), w2 = *(const f32x2*)(ck + 2 * D + c0 + 2 * e);
;                 const float lo = bflo(bq[hf][e]) * (w0[0] * (bflo(cp[hf][e]) * bflo(vp[hf][e])) + w1[0] * (bflo(cq[hf][e]) * bflo(vq[hf][e])) + w2[0] * (bflo(cn[hf][e]) * bflo(vn[hf][e])));
;                 const float hi = bfhi(bq[hf][e]) * (w0[1] * (bfhi(cp[hf][e]) * bfhi(vp[hf][e])) + w1[1] * (bfhi(cq[hf][e]) * bfhi(vq[hf][e])) + w2[1] * (bfhi(cn[hf][e]) * bfhi(vn[hf][e])));
;                 ow[e] = cvt_pk_bf16(lo, hi);
;             }
;             *(u32x4*)(H + (size_t)row * D + c0) = ow;
.Lcg9_nn7:
	v_lshlrev_b32_e32 v202, 16, v176
	v_and_b32_e32 v203, s14, v176
	v_pk_mul_f32 v[234:235], v[234:235], v[202:203]
	v_lshlrev_b32_e32 v206, 16, v177
	v_and_b32_e32 v207, s14, v177
	v_pk_mul_f32 v[236:237], v[236:237], v[206:207]
	v_lshlrev_b32_e32 v210, 16, v178
	v_and_b32_e32 v211, s14, v178
	v_pk_mul_f32 v[238:239], v[238:239], v[210:211]
	v_lshlrev_b32_e32 v202, 16, v179
	v_and_b32_e32 v203, s14, v179
	v_pk_mul_f32 v[240:241], v[240:241], v[202:203]
	v_lshlrev_b32_e32 v206, 16, v180
	v_and_b32_e32 v207, s14, v180
	v_pk_mul_f32 v[242:243], v[242:243], v[206:207]
	v_lshlrev_b32_e32 v210, 16, v181
	v_and_b32_e32 v211, s14, v181
	v_pk_mul_f32 v[244:245], v[244:245], v[210:211]
	v_lshlrev_b32_e32 v202, 16, v182
	v_and_b32_e32 v203, s14, v182
	v_pk_mul_f32 v[246:247], v[246:247], v[202:203]
	v_lshlrev_b32_e32 v206, 16, v183
	v_and_b32_e32 v207, s14, v183
	v_pk_mul_f32 v[248:249], v[248:249], v[206:207]
	v_cvt_pk_bf16_f32 v84, v234, v235
	v_cvt_pk_bf16_f32 v85, v236, v237
	v_cvt_pk_bf16_f32 v86, v238, v239
	v_cvt_pk_bf16_f32 v87, v240, v241
	v_cvt_pk_bf16_f32 v88, v242, v243
	v_cvt_pk_bf16_f32 v89, v244, v245
	v_cvt_pk_bf16_f32 v90, v246, v247
	v_cvt_pk_bf16_f32 v91, v248, v249
	global_store_dwordx4 v1, v[84:87], s[8:9]
	global_store_dwordx4 v1, v[88:91], s[8:9] offset:1024
	s_add_u32 s8, s8, 0x800
	s_addc_u32 s9, s9, 0
	s_waitcnt vmcnt(4)
	v_lshlrev_b32_e32 v202, 16, v130
	v_and_b32_e32 v203, s14, v130
	v_lshlrev_b32_e32 v204, 16, v138
	v_and_b32_e32 v205, s14, v138
	v_pk_mul_f32 v[68:69], v[202:203], v[204:205]
	v_lshlrev_b32_e32 v206, 16, v131
	v_and_b32_e32 v207, s14, v131
	v_lshlrev_b32_e32 v208, 16, v139
	v_and_b32_e32 v209, s14, v139
	v_pk_mul_f32 v[70:71], v[206:207], v[208:209]
	v_lshlrev_b32_e32 v210, 16, v132
	v_and_b32_e32 v211, s14, v132
	v_lshlrev_b32_e32 v212, 16, v140
	v_and_b32_e32 v213, s14, v140
	v_pk_mul_f32 v[72:73], v[210:211], v[212:213]
	v_lshlrev_b32_e32 v202, 16, v133
	v_and_b32_e32 v203, s14, v133
	v_lshlrev_b32_e32 v204, 16, v141
	v_and_b32_e32 v205, s14, v141
	v_pk_mul_f32 v[74:75], v[202:203], v[204:205]
	v_lshlrev_b32_e32 v206, 16, v134
	v_and_b32_e32 v207, s14, v134
	v_lshlrev_b32_e32 v208, 16, v142
	v_and_b32_e32 v209, s14, v142
	v_pk_mul_f32 v[76:77], v[206:207], v[208:209]
	v_lshlrev_b32_e32 v210, 16, v135
	v_and_b32_e32 v211, s14, v135
	v_lshlrev_b32_e32 v212, 16, v143
	v_and_b32_e32 v213, s14, v143
	v_pk_mul_f32 v[78:79], v[210:211], v[212:213]
	v_lshlrev_b32_e32 v202, 16, v136
	v_and_b32_e32 v203, s14, v136
	v_lshlrev_b32_e32 v204, 16, v144
	v_and_b32_e32 v205, s14, v144
	v_pk_mul_f32 v[80:81], v[202:203], v[204:205]
	v_lshlrev_b32_e32 v206, 16, v137
	v_and_b32_e32 v207, s14, v137
	v_lshlrev_b32_e32 v208, 16, v145
	v_and_b32_e32 v209, s14, v145
	v_pk_mul_f32 v[82:83], v[206:207], v[208:209]
	s_add_i32 s12, s11, 8
	s_cmp_lt_u32 s12, 0x4000
	s_cselect_b32 s29, s3, s13
	s_and_b32 s27, s12, s29
	v_pk_mul_f32 v[234:235], v[20:21], v[52:53]
	v_pk_mul_f32 v[236:237], v[22:23], v[54:55]
	v_pk_mul_f32 v[238:239], v[24:25], v[56:57]
	v_pk_mul_f32 v[240:241], v[26:27], v[58:59]
	v_pk_mul_f32 v[242:243], v[28:29], v[60:61]
	v_pk_mul_f32 v[244:245], v[30:31], v[62:63]
	v_pk_mul_f32 v[246:247], v[32:33], v[64:65]
	v_pk_mul_f32 v[248:249], v[34:35], v[66:67]
	s_cmp_eq_u32 s27, 0
	s_cbranch_scc1 .Lcg9_np8
	v_pk_fma_f32 v[234:235], v[4:5], v[98:99], v[234:235]
	v_pk_fma_f32 v[236:237], v[6:7], v[100:101], v[236:237]
	v_pk_fma_f32 v[238:239], v[8:9], v[102:103], v[238:239]
	v_pk_fma_f32 v[240:241], v[10:11], v[104:105], v[240:241]
	v_pk_fma_f32 v[242:243], v[12:13], v[106:107], v[242:243]
	v_pk_fma_f32 v[244:245], v[14:15], v[108:109], v[244:245]
	v_pk_fma_f32 v[246:247], v[16:17], v[110:111], v[246:247]
	v_pk_fma_f32 v[248:249], v[18:19], v[112:113], v[248:249]

; __device__ __forceinline__ unsigned cvt_pk_bf16(float lo, float hi) { unsigned r; asm volatile("v_cvt_pk_bf16_f32 %0, %1, %2" : "=v"(r) : "v"(lo), "v"(hi)); return r; }
; __device__ __forceinline__ float bflo(unsigned w) { return __uint_as_float(w << 16); }
; __device__ __forceinline__ float bfhi(unsigned w) { return __uint_as_float(w & 0xffff0000u); }
; __device__ __forceinline__ void convgate_phase(const bf16_t* U, bf16_t* H, int rows, const float* ck, int gw, int NGW, int lane) {
;     ...
;             for (int e = 0; e < 4; ++e) {
;                 const f32x2 w0 = *(const f32x2*)(ck + c0 + 2 * e), w1 = *(const f32x2*)(ck + D + c0 + 2 * e), w2 = *(const f32x2*)(ck + 2 * D + c0 + 2 * e);
;                 const float lo = bflo(bq[hf][e]) * (w0[0] * (bflo(cp[hf][e]) * bflo(vp[hf][e])) + w1[0] * (bflo(cq[hf][e]) * bflo(vq[hf][e])) + w2[0] * (bflo(cn[hf][e]) * bflo(vn[hf][e])));
;                 const float hi = bfhi(bq[hf][e]) * (w0[1] * (bfhi(cp[hf][e]) * bfhi(vp[hf][e])) + w1[1] * (bfhi(cq[hf][e]) * bfhi(vq[hf][e])) + w2[1] * (bfhi(cn[hf][e]) * bfhi(vn[hf][e])));
;                 ow[e] = cvt_pk_bf16(lo, hi);
;             }
;             *(u32x4*)(H + (size_t)row * D + c0) = ow;
.Lcg9_nn8:
	v_lshlrev_b32_e32 v202, 16, v226
	v_and_b32_e32 v203, s14, v226
	v_pk_mul_f32 v[234:235], v[234:235], v[202:203]
	v_lshlrev_b32_e32 v206, 16, v227
	v_and_b32_e32 v207, s14, v227
	v_pk_mul_f32 v[236:237], v[236:237], v[206:207]
	v_lshlrev_b32_e32 v210, 16, v228
	v_and_b32_e32 v211, s14, v228
	v_pk_mul_f32 v[238:239], v[238:239], v[210:211]
	v_lshlrev_b32_e32 v202, 16, v229
	v_and_b32_e32 v203, s14, v229
	v_pk_mul_f32 v[240:241], v[240:241], v[202:203]
	v_lshlrev_b32_e32 v206, 16, v230
	v_and_b32_e32 v207, s14, v230
	v_pk_mul_f32 v[242:243], v[242:243], v[206:207]
	v_lshlrev_b32_e32 v210, 16, v231
	v_and_b32_e32 v211, s14, v231
	v_pk_mul_f32 v[244:245], v[244:245], v[210:211]
	v_lshlrev_b32_e32 v202, 16, v232
	v_and_b32_e32 v203, s14, v232
	v_pk_mul_f32 v[246:247], v[246:247], v[202:203]
	v_lshlrev_b32_e32 v206, 16, v233
	v_and_b32_e32 v207, s14, v233
	v_pk_mul_f32 v[248:249], v[248:249], v[206:207]
	v_cvt_pk_bf16_f32 v84, v234, v235
	v_cvt_pk_bf16_f32 v85, v236, v237
	v_cvt_pk_bf16_f32 v86, v238, v239
	v_cvt_pk_bf16_f32 v87, v240, v241
	v_cvt_pk_bf16_f32 v88, v242, v243
	v_cvt_pk_bf16_f32 v89, v244, v245
	v_cvt_pk_bf16_f32 v90, v246, v247
	v_cvt_pk_bf16_f32 v91, v248, v249
	global_store_dwordx4 v1, v[84:87], s[8:9]
	global_store_dwordx4 v1, v[88:91], s[8:9] offset:1024
	s_add_u32 s8, s8, 0x800
	s_addc_u32 s9, s9, 0
	s_branch .Lcg_done

; __device__ __forceinline__ unsigned cvt_pk_bf16(float lo, float hi) { unsigned r; asm volatile("v_cvt_pk_bf16_f32 %0, %1, %2" : "=v"(r) : "v"(lo), "v"(hi)); return r; }
; __device__ __forceinline__ float bflo(unsigned w) { return __uint_as_float(w << 16); }
; __device__ __forceinline__ float bfhi(unsigned w) { return __uint_as_float(w & 0xffff0000u); }
; __device__ __forceinline__ void convgate_phase(const bf16_t* U, bf16_t* H, int rows, const float* ck, int gw, int NGW, int lane) {
;     ...
;             for (int e = 0; e < 4; ++e) {
;                 const f32x2 w0 = *(const f32x2*)(ck + c0 + 2 * e), w1 = *(const f32x2*)(ck + D + c0 + 2 * e), w2 = *(const f32x2*)(ck + 2 * D + c0 + 2 * e);
;                 const float lo = bflo(bq[hf][e]) * (w0[0] * (bflo(cp[hf][e]) * bflo(vp[hf][e])) + w1[0] * (bflo(cq[hf][e]) * bflo(vq[hf][e])) + w2[0] * (bflo(cn[hf][e]) * bflo(vn[hf][e])));
;                 const float hi = bfhi(bq[hf][e]) * (w0[1] * (bfhi(cp[hf][e]) * bfhi(vp[hf][e])) + w1[1] * (bfhi(cq[hf][e]) * bfhi(vq[hf][e])) + w2[1] * (bfhi(cn[hf][e]) * bfhi(vn[hf][e])));
;                 ow[e] = cvt_pk_bf16(lo, hi);
;             }
;             *(u32x4*)(H + (size_t)row * D + c0) = ow;
.Lcg8_nn4:
	v_lshlrev_b32_e32 v202, 16, v176
	v_and_b32_e32 v203, s14, v176
	v_pk_mul_f32 v[234:235], v[234:235], v[202:203]
	v_lshlrev_b32_e32 v206, 16, v177
	v_and_b32_e32 v207, s14, v177
	v_pk_mul_f32 v[236:237], v[236:237], v[206:207]
	v_lshlrev_b32_e32 v210, 16, v178
	v_and_b32_e32 v211, s14, v178
	v_pk_mul_f32 v[238:239], v[238:239], v[210:211]
	v_lshlrev_b32_e32 v202, 16, v179
	v_and_b32_e32 v203, s14, v179
	v_pk_mul_f32 v[240:241], v[240:241], v[202:203]
	v_lshlrev_b32_e32 v206, 16, v180
	v_and_b32_e32 v207, s14, v180
	v_pk_mul_f32 v[242:243], v[242:243], v[206:207]
	v_lshlrev_b32_e32 v210, 16, v181
	v_and_b32_e32 v211, s14, v181
	v_pk_mul_f32 v[244:245], v[244:245], v[210:211]
	v_lshlrev_b32_e32 v202, 16, v182
	v_and_b32_e32 v203, s14, v182
	v_pk_mul_f32 v[246:247], v[246:247], v[202:203]
	v_lshlrev_b32_e32 v206, 16, v183
	v_and_b32_e32 v207, s14, v183
	v_pk_mul_f32 v[248:249], v[248:249], v[206:207]
	v_cvt_pk_bf16_f32 v84, v234, v235
	v_cvt_pk_bf16_f32 v85, v236, v237
	v_cvt_pk_bf16_f32 v86, v238, v239
	v_cvt_pk_bf16_f32 v87, v240, v241
	v_cvt_pk_bf16_f32 v88, v242, v243
	v_cvt_pk_bf16_f32 v89, v244, v245
	v_cvt_pk_bf16_f32 v90, v246, v247
	v_cvt_pk_bf16_f32 v91, v248, v249
	global_store_dwordx4 v1, v[84:87], s[8:9]
	global_store_dwordx4 v1, v[88:91], s[8:9] offset:1024
	s_add_u32 s8, s8, 0x800
	s_addc_u32 s9, s9, 0
	global_load_dwordx4 v[176:179], v1, s[6:7] nt
	global_load_dwordx4 v[180:183], v1, s[6:7] offset:1024 nt
	s_add_u32 s6, s6, 0x1800
	s_addc_u32 s7, s7, 0
	s_waitcnt vmcnt(16)
	v_lshlrev_b32_e32 v202, 16, v130
	v_and_b32_e32 v203, s14, v130
	v_lshlrev_b32_e32 v204, 16, v138
	v_and_b32_e32 v205, s14, v138
	v_pk_mul_f32 v[68:69], v[202:203], v[204:205]
	v_lshlrev_b32_e32 v206, 16, v131
	v_and_b32_e32 v207, s14, v131
	v_lshlrev_b32_e32 v208, 16, v139
	v_and_b32_e32 v209, s14, v139
	v_pk_mul_f32 v[70:71], v[206:207], v[208:209]
	v_lshlrev_b32_e32 v210, 16, v132
	v_and_b32_e32 v211, s14, v132
	v_lshlrev_b32_e32 v212, 16, v140
	v_and_b32_e32 v213, s14, v140
	v_pk_mul_f32 v[72:73], v[210:211], v[212:213]
	v_lshlrev_b32_e32 v202, 16, v133
	v_and_b32_e32 v203, s14, v133
	v_lshlrev_b32_e32 v204, 16, v141
	v_and_b32_e32 v205, s14, v141
	v_pk_mul_f32 v[74:75], v[202:203], v[204:205]
	v_lshlrev_b32_e32 v206, 16, v134
	v_and_b32_e32 v207, s14, v134
	v_lshlrev_b32_e32 v208, 16, v142
	v_and_b32_e32 v209, s14, v142
	v_pk_mul_f32 v[76:77], v[206:207], v[208:209]
	v_lshlrev_b32_e32 v210, 16, v135
	v_and_b32_e32 v211, s14, v135
	v_lshlrev_b32_e32 v212, 16, v143
	v_and_b32_e32 v213, s14, v143
	v_pk_mul_f32 v[78:79], v[210:211], v[212:213]
	v_lshlrev_b32_e32 v202, 16, v136
	v_and_b32_e32 v203, s14, v136
	v_lshlrev_b32_e32 v204, 16, v144
	v_and_b32_e32 v205, s14, v144
	v_pk_mul_f32 v[80:81], v[202:203], v[204:205]
	v_lshlrev_b32_e32 v206, 16, v137
	v_and_b32_e32 v207, s14, v137
	v_lshlrev_b32_e32 v208, 16, v145
	v_and_b32_e32 v209, s14, v145
	v_pk_mul_f32 v[82:83], v[206:207], v[208:209]
	s_add_i32 s12, s11, 5
	s_cmp_lt_u32 s12, 0x4000
	s_cselect_b32 s29, s3, s13
	s_and_b32 s27, s12, s29
	v_pk_mul_f32 v[234:235], v[20:21], v[52:53]
	v_pk_mul_f32 v[236:237], v[22:23], v[54:55]
	v_pk_mul_f32 v[238:239], v[24:25], v[56:57]
	v_pk_mul_f32 v[240:241], v[26:27], v[58:59]
	v_pk_mul_f32 v[242:243], v[28:29], v[60:61]
	v_pk_mul_f32 v[244:245], v[30:31], v[62:63]
	v_pk_mul_f32 v[246:247], v[32:33], v[64:65]
	v_pk_mul_f32 v[248:249], v[34:35], v[66:67]
	s_cmp_eq_u32 s27, 0
	s_cbranch_scc1 .Lcg8_np5
	v_pk_fma_f32 v[234:235], v[4:5], v[98:99], v[234:235]
	v_pk_fma_f32 v[236:237], v[6:7], v[100:101], v[236:237]
	v_pk_fma_f32 v[238:239], v[8:9], v[102:103], v[238:239]
	v_pk_fma_f32 v[240:241], v[10:11], v[104:105], v[240:241]
	v_pk_fma_f32 v[242:243], v[12:13], v[106:107], v[242:243]
	v_pk_fma_f32 v[244:245], v[14:15], v[108:109], v[244:245]
	v_pk_fma_f32 v[246:247], v[16:17], v[110:111], v[246:247]
	v_pk_fma_f32 v[248:249], v[18:19], v[112:113], v[248:249]

; __device__ __forceinline__ unsigned cvt_pk_bf16(float lo, float hi) { unsigned r; asm volatile("v_cvt_pk_bf16_f32 %0, %1, %2" : "=v"(r) : "v"(lo), "v"(hi)); return r; }
; __device__ __forceinline__ float bflo(unsigned w) { return __uint_as_float(w << 16); }
; __device__ __forceinline__ float bfhi(unsigned w) { return __uint_as_float(w & 0xffff0000u); }
; __device__ __forceinline__ void convgate_phase(const bf16_t* U, bf16_t* H, int rows, const float* ck, int gw, int NGW, int lane) {
;     ...
;             for (int e = 0; e < 4; ++e) {
;                 const f32x2 w0 = *(const f32x2*)(ck + c0 + 2 * e), w1 = *(const f32x2*)(ck + D + c0 + 2 * e), w2 = *(const f32x2*)(ck + 2 * D + c0 + 2 * e);
;                 const float lo = bflo(bq[hf][e]) * (w0[0] * (bflo(cp[hf][e]) * bflo(vp[hf][e])) + w1[0] * (bflo(cq[hf][e]) * bflo(vq[hf][e])) + w2[0] * (bflo(cn[hf][e]) * bflo(vn[hf][e])));
;                 const float hi = bfhi(bq[hf][e]) * (w0[1] * (bfhi(cp[hf][e]) * bfhi(vp[hf][e])) + w1[1] * (bfhi(cq[hf][e]) * bfhi(vq[hf][e])) + w2[1] * (bfhi(cn[hf][e]) * bfhi(vn[hf][e])));
;                 ow[e] = cvt_pk_bf16(lo, hi);
;             }
;             *(u32x4*)(H + (size_t)row * D + c0) = ow;
.Lcg8_nn5:
	v_lshlrev_b32_e32 v202, 16, v226
	v_and_b32_e32 v203, s14, v226
	v_pk_mul_f32 v[234:235], v[234:235], v[202:203]
	v_lshlrev_b32_e32 v206, 16, v227
	v_and_b32_e32 v207, s14, v227
	v_pk_mul_f32 v[236:237], v[236:237], v[206:207]
	v_lshlrev_b32_e32 v210, 16, v228
	v_and_b32_e32 v211, s14, v228
	v_pk_mul_f32 v[238:239], v[238:239], v[210:211]
	v_lshlrev_b32_e32 v202, 16, v229
	v_and_b32_e32 v203, s14, v229
	v_pk_mul_f32 v[240:241], v[240:241], v[202:203]
	v_lshlrev_b32_e32 v206, 16, v230
	v_and_b32_e32 v207, s14, v230
	v_pk_mul_f32 v[242:243], v[242:243], v[206:207]
	v_lshlrev_b32_e32 v210, 16, v231
	v_and_b32_e32 v211, s14, v231
	v_pk_mul_f32 v[244:245], v[244:245], v[210:211]
	v_lshlrev_b32_e32 v202, 16, v232
	v_and_b32_e32 v203, s14, v232
	v_pk_mul_f32 v[246:247], v[246:247], v[202:203]
	v_lshlrev_b32_e32 v206, 16, v233
	v_and_b32_e32 v207, s14, v233
	v_pk_mul_f32 v[248:249], v[248:249], v[206:207]
	v_cvt_pk_bf16_f32 v84, v234, v235
	v_cvt_pk_bf16_f32 v85, v236, v237
	v_cvt_pk_bf16_f32 v86, v238, v239
	v_cvt_pk_bf16_f32 v87, v240, v241
	v_cvt_pk_bf16_f32 v88, v242, v243
	v_cvt_pk_bf16_f32 v89, v244, v245
	v_cvt_pk_bf16_f32 v90, v246, v247
	v_cvt_pk_bf16_f32 v91, v248, v249
	global_store_dwordx4 v1, v[84:87], s[8:9]
	global_store_dwordx4 v1, v[88:91], s[8:9] offset:1024
	s_add_u32 s8, s8, 0x800
	s_addc_u32 s9, s9, 0
	s_waitcnt vmcnt(10)
	v_lshlrev_b32_e32 v202, 16, v160
	v_and_b32_e32 v203, s14, v160
	v_lshlrev_b32_e32 v204, 16, v168
	v_and_b32_e32 v205, s14, v168
	v_pk_mul_f32 v[98:99], v[202:203], v[204:205]
	v_lshlrev_b32_e32 v206, 16, v161
	v_and_b32_e32 v207, s14, v161
	v_lshlrev_b32_e32 v208, 16, v169
	v_and_b32_e32 v209, s14, v169
	v_pk_mul_f32 v[100:101], v[206:207], v[208:209]
	v_lshlrev_b32_e32 v210, 16, v162
	v_and_b32_e32 v211, s14, v162
	v_lshlrev_b32_e32 v212, 16, v170
	v_and_b32_e32 v213, s14, v170
	v_pk_mul_f32 v[102:103], v[210:211], v[212:213]
	v_lshlrev_b32_e32 v202, 16, v163
	v_and_b32_e32 v203, s14, v163
	v_lshlrev_b32_e32 v204, 16, v171
	v_and_b32_e32 v205, s14, v171
	v_pk_mul_f32 v[104:105], v[202:203], v[204:205]
	v_lshlrev_b32_e32 v206, 16, v164
	v_and_b32_e32 v207, s14, v164
	v_lshlrev_b32_e32 v208, 16, v172
	v_and_b32_e32 v209, s14, v172
	v_pk_mul_f32 v[106:107], v[206:207], v[208:209]
	v_lshlrev_b32_e32 v210, 16, v165
	v_and_b32_e32 v211, s14, v165
	v_lshlrev_b32_e32 v212, 16, v173
	v_and_b32_e32 v213, s14, v173
	v_pk_mul_f32 v[108:109], v[210:211], v[212:213]
	v_lshlrev_b32_e32 v202, 16, v166
	v_and_b32_e32 v203, s14, v166
	v_lshlrev_b32_e32 v204, 16, v174
	v_and_b32_e32 v205, s14, v174
	v_pk_mul_f32 v[110:111], v[202:203], v[204:205]
	v_lshlrev_b32_e32 v206, 16, v167
	v_and_b32_e32 v207, s14, v167
	v_lshlrev_b32_e32 v208, 16, v175
	v_and_b32_e32 v209, s14, v175
	v_pk_mul_f32 v[112:113], v[206:207], v[208:209]
	s_add_i32 s12, s11, 6
	s_cmp_lt_u32 s12, 0x4000
	s_cselect_b32 s29, s3, s13
	s_and_b32 s27, s12, s29
	v_pk_mul_f32 v[234:235], v[20:21], v[68:69]
	v_pk_mul_f32 v[236:237], v[22:23], v[70:71]
	v_pk_mul_f32 v[238:239], v[24:25], v[72:73]
	v_pk_mul_f32 v[240:241], v[26:27], v[74:75]
	v_pk_mul_f32 v[242:243], v[28:29], v[76:77]
	v_pk_mul_f32 v[244:245], v[30:31], v[78:79]
	v_pk_mul_f32 v[246:247], v[32:33], v[80:81]
	v_pk_mul_f32 v[248:249], v[34:35], v[82:83]
	s_cmp_eq_u32 s27, 0
	s_cbranch_scc1 .Lcg8_np6
	v_pk_fma_f32 v[234:235], v[4:5], v[52:53], v[234:235]
	v_pk_fma_f32 v[236:237], v[6:7], v[54:55], v[236:237]
	v_pk_fma_f32 v[238:239], v[8:9], v[56:57], v[238:239]
	v_pk_fma_f32 v[240:241], v[10:11], v[58:59], v[240:241]
	v_pk_fma_f32 v[242:243], v[12:13], v[60:61], v[242:243]
	v_pk_fma_f32 v[244:245], v[14:15], v[62:63], v[244:245]
	v_pk_fma_f32 v[246:247], v[16:17], v[64:65], v[246:247]
	v_pk_fma_f32 v[248:249], v[18:19], v[66:67], v[248:249]

; __device__ __forceinline__ unsigned cvt_pk_bf16(float lo, float hi) { unsigned r; asm volatile("v_cvt_pk_bf16_f32 %0, %1, %2" : "=v"(r) : "v"(lo), "v"(hi)); return r; }
; __device__ __forceinline__ float bflo(unsigned w) { return __uint_as_float(w << 16); }
; __device__ __forceinline__ float bfhi(unsigned w) { return __uint_as_float(w & 0xffff0000u); }
; __device__ __forceinline__ void convgate_phase(const bf16_t* U, bf16_t* H, int rows, const float* ck, int gw, int NGW, int lane) {
;     ...
;             for (int e = 0; e < 4; ++e) {
;                 const f32x2 w0 = *(const f32x2*)(ck + c0 + 2 * e), w1 = *(const f32x2*)(ck + D + c0 + 2 * e), w2 = *(const f32x2*)(ck + 2 * D + c0 + 2 * e);
;                 const float lo = bflo(bq[hf][e]) * (w0[0] * (bflo(cp[hf][e]) * bflo(vp[hf][e])) + w1[0] * (bflo(cq[hf][e]) * bflo(vq[hf][e])) + w2[0] * (bflo(cn[hf][e]) * bflo(vn[hf][e])));
;                 const float hi = bfhi(bq[hf][e]) * (w0[1] * (bfhi(cp[hf][e]) * bfhi(vp[hf][e])) + w1[1] * (bfhi(cq[hf][e]) * bfhi(vq[hf][e])) + w2[1] * (bfhi(cn[hf][e]) * bfhi(vn[hf][e])));
;                 ow[e] = cvt_pk_bf16(lo, hi);
;             }
;             *(u32x4*)(H + (size_t)row * D + c0) = ow;
.Lcg8_nn6:
	v_lshlrev_b32_e32 v202, 16, v146
	v_and_b32_e32 v203, s14, v146
	v_pk_mul_f32 v[234:235], v[234:235], v[202:203]
	v_lshlrev_b32_e32 v206, 16, v147
	v_and_b32_e32 v207, s14, v147
	v_pk_mul_f32 v[236:237], v[236:237], v[206:207]
	v_lshlrev_b32_e32 v210, 16, v148
	v_and_b32_e32 v211, s14, v148
	v_pk_mul_f32 v[238:239], v[238:239], v[210:211]
	v_lshlrev_b32_e32 v202, 16, v149
	v_and_b32_e32 v203, s14, v149
	v_pk_mul_f32 v[240:241], v[240:241], v[202:203]
	v_lshlrev_b32_e32 v206, 16, v150
	v_and_b32_e32 v207, s14, v150
	v_pk_mul_f32 v[242:243], v[242:243], v[206:207]
	v_lshlrev_b32_e32 v210, 16, v151
	v_and_b32_e32 v211, s14, v151
	v_pk_mul_f32 v[244:245], v[244:245], v[210:211]
	v_lshlrev_b32_e32 v202, 16, v152
	v_and_b32_e32 v203, s14, v152
	v_pk_mul_f32 v[246:247], v[246:247], v[202:203]
	v_lshlrev_b32_e32 v206, 16, v153
	v_and_b32_e32 v207, s14, v153
	v_pk_mul_f32 v[248:249], v[248:249], v[206:207]
	v_cvt_pk_bf16_f32 v84, v234, v235
	v_cvt_pk_bf16_f32 v85, v236, v237
	v_cvt_pk_bf16_f32 v86, v238, v239
	v_cvt_pk_bf16_f32 v87, v240, v241
	v_cvt_pk_bf16_f32 v88, v242, v243
	v_cvt_pk_bf16_f32 v89, v244, v245
	v_cvt_pk_bf16_f32 v90, v246, v247
	v_cvt_pk_bf16_f32 v91, v248, v249
	global_store_dwordx4 v1, v[84:87], s[8:9]
	global_store_dwordx4 v1, v[88:91], s[8:9] offset:1024
	s_add_u32 s8, s8, 0x800
	s_addc_u32 s9, s9, 0
	s_waitcnt vmcnt(4)
	v_lshlrev_b32_e32 v202, 16, v114
	v_and_b32_e32 v203, s14, v114
	v_lshlrev_b32_e32 v204, 16, v122
	v_and_b32_e32 v205, s14, v122
	v_pk_mul_f32 v[52:53], v[202:203], v[204:205]
	v_lshlrev_b32_e32 v206, 16, v115
	v_and_b32_e32 v207, s14, v115
	v_lshlrev_b32_e32 v208, 16, v123
	v_and_b32_e32 v209, s14, v123
	v_pk_mul_f32 v[54:55], v[206:207], v[208:209]
	v_lshlrev_b32_e32 v210, 16, v116
	v_and_b32_e32 v211, s14, v116
	v_lshlrev_b32_e32 v212, 16, v124
	v_and_b32_e32 v213, s14, v124
	v_pk_mul_f32 v[56:57], v[210:211], v[212:213]
	v_lshlrev_b32_e32 v202, 16, v117
	v_and_b32_e32 v203, s14, v117
	v_lshlrev_b32_e32 v204, 16, v125
	v_and_b32_e32 v205, s14, v125
	v_pk_mul_f32 v[58:59], v[202:203], v[204:205]
	v_lshlrev_b32_e32 v206, 16, v118
	v_and_b32_e32 v207, s14, v118
	v_lshlrev_b32_e32 v208, 16, v126
	v_and_b32_e32 v209, s14, v126
	v_pk_mul_f32 v[60:61], v[206:207], v[208:209]
	v_lshlrev_b32_e32 v210, 16, v119
	v_and_b32_e32 v211, s14, v119
	v_lshlrev_b32_e32 v212, 16, v127
	v_and_b32_e32 v213, s14, v127
	v_pk_mul_f32 v[62:63], v[210:211], v[212:213]
	v_lshlrev_b32_e32 v202, 16, v120
	v_and_b32_e32 v203, s14, v120
	v_lshlrev_b32_e32 v204, 16, v128
	v_and_b32_e32 v205, s14, v128
	v_pk_mul_f32 v[64:65], v[202:203], v[204:205]
	v_lshlrev_b32_e32 v206, 16, v121
	v_and_b32_e32 v207, s14, v121
	v_lshlrev_b32_e32 v208, 16, v129
	v_and_b32_e32 v209, s14, v129
	v_pk_mul_f32 v[66:67], v[206:207], v[208:209]
	s_add_i32 s12, s11, 7
	s_cmp_lt_u32 s12, 0x4000
	s_cselect_b32 s29, s3, s13
	s_and_b32 s27, s12, s29
	v_pk_mul_f32 v[234:235], v[20:21], v[98:99]
	v_pk_mul_f32 v[236:237], v[22:23], v[100:101]
	v_pk_mul_f32 v[238:239], v[24:25], v[102:103]
	v_pk_mul_f32 v[240:241], v[26:27], v[104:105]
	v_pk_mul_f32 v[242:243], v[28:29], v[106:107]
	v_pk_mul_f32 v[244:245], v[30:31], v[108:109]
	v_pk_mul_f32 v[246:247], v[32:33], v[110:111]
	v_pk_mul_f32 v[248:249], v[34:35], v[112:113]
	s_cmp_eq_u32 s27, 0
	s_cbranch_scc1 .Lcg8_np7
	v_pk_fma_f32 v[234:235], v[4:5], v[68:69], v[234:235]
	v_pk_fma_f32 v[236:237], v[6:7], v[70:71], v[236:237]
	v_pk_fma_f32 v[238:239], v[8:9], v[72:73], v[238:239]
	v_pk_fma_f32 v[240:241], v[10:11], v[74:75], v[240:241]
	v_pk_fma_f32 v[242:243], v[12:13], v[76:77], v[242:243]
	v_pk_fma_f32 v[244:245], v[14:15], v[78:79], v[244:245]
	v_pk_fma_f32 v[246:247], v[16:17], v[80:81], v[246:247]
	v_pk_fma_f32 v[248:249], v[18:19], v[82:83], v[248:249]

; __device__ __forceinline__ unsigned cvt_pk_bf16(float lo, float hi) { unsigned r; asm volatile("v_cvt_pk_bf16_f32 %0, %1, %2" : "=v"(r) : "v"(lo), "v"(hi)); return r; }
; __device__ __forceinline__ float bflo(unsigned w) { return __uint_as_float(w << 16); }
; __device__ __forceinline__ float bfhi(unsigned w) { return __uint_as_float(w & 0xffff0000u); }
; __device__ __forceinline__ void convgate_phase(const bf16_t* U, bf16_t* H, int rows, const float* ck, int gw, int NGW, int lane) {
;     ...
;             for (int e = 0; e < 4; ++e) {
;                 const f32x2 w0 = *(const f32x2*)(ck + c0 + 2 * e), w1 = *(const f32x2*)(ck + D + c0 + 2 * e), w2 = *(const f32x2*)(ck + 2 * D + c0 + 2 * e);
;                 const float lo = bflo(bq[hf][e]) * (w0[0] * (bflo(cp[hf][e]) * bflo(vp[hf][e])) + w1[0] * (bflo(cq[hf][e]) * bflo(vq[hf][e])) + w2[0] * (bflo(cn[hf][e]) * bflo(vn[hf][e])));
;                 const float hi = bfhi(bq[hf][e]) * (w0[1] * (bfhi(cp[hf][e]) * bfhi(vp[hf][e])) + w1[1] * (bfhi(cq[hf][e]) * bfhi(vq[hf][e])) + w2[1] * (bfhi(cn[hf][e]) * bfhi(vn[hf][e])));
;                 ow[e] = cvt_pk_bf16(lo, hi);
;             }
;             *(u32x4*)(H + (size_t)row * D + c0) = ow;
.Lcg8_nn7:
	v_lshlrev_b32_e32 v202, 16, v176
	v_and_b32_e32 v203, s14, v176
	v_pk_mul_f32 v[234:235], v[234:235], v[202:203]
	v_lshlrev_b32_e32 v206, 16, v177
	v_and_b32_e32 v207, s14, v177
	v_pk_mul_f32 v[236:237], v[236:237], v[206:207]
	v_lshlrev_b32_e32 v210, 16, v178
	v_and_b32_e32 v211, s14, v178
	v_pk_mul_f32 v[238:239], v[238:239], v[210:211]
	v_lshlrev_b32_e32 v202, 16, v179
	v_and_b32_e32 v203, s14, v179
	v_pk_mul_f32 v[240:241], v[240:241], v[202:203]
	v_lshlrev_b32_e32 v206, 16, v180
	v_and_b32_e32 v207, s14, v180
	v_pk_mul_f32 v[242:243], v[242:243], v[206:207]
	v_lshlrev_b32_e32 v210, 16, v181
	v_and_b32_e32 v211, s14, v181
	v_pk_mul_f32 v[244:245], v[244:245], v[210:211]
	v_lshlrev_b32_e32 v202, 16, v182
	v_and_b32_e32 v203, s14, v182
	v_pk_mul_f32 v[246:247], v[246:247], v[202:203]
	v_lshlrev_b32_e32 v206, 16, v183
	v_and_b32_e32 v207, s14, v183
	v_pk_mul_f32 v[248:249], v[248:249], v[206:207]
	v_cvt_pk_bf16_f32 v84, v234, v235
	v_cvt_pk_bf16_f32 v85, v236, v237
	v_cvt_pk_bf16_f32 v86, v238, v239
	v_cvt_pk_bf16_f32 v87, v240, v241
	v_cvt_pk_bf16_f32 v88, v242, v243
	v_cvt_pk_bf16_f32 v89, v244, v245
	v_cvt_pk_bf16_f32 v90, v246, v247
	v_cvt_pk_bf16_f32 v91, v248, v249
	global_store_dwordx4 v1, v[84:87], s[8:9]
	global_store_dwordx4 v1, v[88:91], s[8:9] offset:1024
	s_add_u32 s8, s8, 0x800
	s_addc_u32 s9, s9, 0
	s_branch .Lcg_done
